# hand-scheduled latent-attention key loop: 3-stage LDS ring, K rows padded to 224 B (conflict-free ds_read_b128), V fragments via ds_read_b64 pairs
# speedup vs baseline: 1.0809x; 1.0031x over previous
; DEV void attn_item(const Params& p, int bl, int head, int q0, int nkeys, char* smem, int tid) {
;     ...
;   for (int i = 0; i < 3; ++i) { int c = i * 512 + tid; koff[i] = (c / 12) * KROW + (c % 12) * 16; }
; #pragma unroll
;   for (int i = 0; i < 2; ++i) { int c = i * 512 + tid; voffg[i] = (c >> 4) * NTOK + (c & 15) * 8; voffl[i] = (c >> 4) * VROW + (c & 15) * 16; }
;   __syncthreads();
; #pragma unroll
;   for (int i = 0; i < 3; ++i) kr[i] = *(const u32x4*)(Kg + (long)(i * 512 + tid) * 8);
; #pragma unroll
;   for (int i = 0; i < 2; ++i) vr[i] = *(const u32x4*)(Vg + voffg[i]);
; #pragma unroll
;   for (int i = 0; i < 3; ++i) *(u32x4*)(smem + koff[i]) = kr[i];
; #pragma unroll
;   for (int i = 0; i < 2; ++i) *(u32x4*)(smem + KBYTES + voffl[i]) = vr[i];
;     ...
;   for (int t = 0; t < nt; ++t) {
;     if (t + 1 < nt) {
; #pragma unroll
;       for (int i = 0; i < 3; ++i) kr[i] = *(const u32x4*)(Kg + (long)(t + 1) * 128 * 96 + (long)(i * 512 + tid) * 8);
; #pragma unroll
;       for (int i = 0; i < 2; ++i) vr[i] = *(const u32x4*)(Vg + (t + 1) * 128 + voffg[i]);
;     }
;     const char* kb = smem + (t & 1) * ASTG;
;     const char* vb = kb + KBYTES;
; #pragma unroll
;     for (int hh = 0; hh < 2; ++hh) {
;       f32x4 s[4][2];
; #pragma unroll
;       for (int kf = 0; kf < 4; ++kf) {
; #pragma unroll
;         for (int ks = 0; ks < 3; ++ks) {
;           bf16x8 a = *(const bf16x8*)(kb + (hh * 64 + kf * 16 + fr) * KROW + ks * 64 + fq * 16);
;           s[kf][0] = __builtin_amdgcn_mfma_f32_16x16x32_bf16(a, qf[0][ks], ks == 0 ? negm[0] : s[kf][0], 0, 0, 0);
;           s[kf][1] = __builtin_amdgcn_mfma_f32_16x16x32_bf16(a, qf[1][ks], ks == 0 ? negm[1] : s[kf][1], 0, 0, 0);
;         }
;       }
.LBB0_990:
	s_mov_b32 s77, s76
	s_mov_b32 s78, s76
	s_mov_b32 s79, s76
	v_mov_b32_e32 v152, s76
	v_mov_b32_e32 v153, s76
	v_mov_b32_e32 v154, s76
	v_mov_b32_e32 v155, s76
	s_mov_b32 s12, 0
	s_mov_b32 s9, 0xb400
	s_mov_b32 s15, 0x16800
	s_mov_b32 s16, 0x6000
	s_mov_b32 s17, 0
	s_mov_b32 s13, 0
	v_mul_u32_u24_e32 v181, 0xe0, v175
	s_mov_b32 s18, 0x15555556
	v_mov_b32_e32 v189, v197
	v_mul_hi_u32 v190, v189, s18
	v_lshlrev_b32_e32 v189, 4, v189
	v_lshl_add_u32 v190, v190, 5, v189
	v_add_u32_e32 v189, 512, v197
	v_mul_hi_u32 v191, v189, s18
	v_lshlrev_b32_e32 v189, 4, v189
	v_lshl_add_u32 v191, v191, 5, v189
	v_add_u32_e32 v189, 1024, v197
	v_mul_hi_u32 v192, v189, s18
	v_lshlrev_b32_e32 v189, 4, v189
	v_lshl_add_u32 v192, v192, 5, v189
	global_load_dwordx4 v[230:233], v[164:165], off
	global_load_dwordx4 v[234:237], v[166:167], off
	global_load_dwordx4 v[238:241], v[168:169], off
	global_load_dwordx4 v[242:245], v[170:171], off
	global_load_dwordx4 v[246:249], v[172:173], off
	v_lshl_add_u64 v[164:165], v[164:165], 0, s[26:27]
	v_lshl_add_u64 v[166:167], v[166:167], 0, s[26:27]
	v_lshl_add_u64 v[168:169], v[168:169], 0, s[16:17]
	v_lshl_add_u64 v[170:171], v[170:171], 0, s[16:17]
	v_lshl_add_u64 v[172:173], v[172:173], 0, s[16:17]
	v_add_u32_e32 v184, s9, v190
	v_add_u32_e32 v185, s9, v191
	v_add_u32_e32 v186, s9, v192
	v_add_u32_e32 v187, s9, v160
	v_add_u32_e32 v188, s9, v162
	v_add3_u32 v179, s12, v156, v178
	ds_read_b128 v[198:201], v179
	ds_read_b128 v[202:205], v179 offset:3328
	ds_read_b128 v[206:209], v179 offset:6656
	ds_read_b128 v[210:213], v179 offset:9984
	ds_read_b128 v[214:217], v179 offset:64
	ds_read_b128 v[218:221], v179 offset:3392
	ds_read_b128 v[222:225], v179 offset:6720
	ds_read_b128 v[226:229], v179 offset:10048
	s_waitcnt lgkmcnt(7)
	v_mfma_f32_16x16x32_bf16 v[72:75], v[198:201], v[12:15], v[24:27]
	v_mfma_f32_16x16x32_bf16 v[76:79], v[198:201], v[20:23], v[28:31]
	ds_read_b128 v[198:201], v179 offset:128
	s_waitcnt lgkmcnt(7)
	v_mfma_f32_16x16x32_bf16 v[80:83], v[202:205], v[12:15], v[24:27]
	v_mfma_f32_16x16x32_bf16 v[84:87], v[202:205], v[20:23], v[28:31]
	ds_read_b128 v[202:205], v179 offset:3456
	s_waitcnt lgkmcnt(7)
	v_mfma_f32_16x16x32_bf16 v[88:91], v[206:209], v[12:15], v[24:27]
	v_mfma_f32_16x16x32_bf16 v[92:95], v[206:209], v[20:23], v[28:31]
	ds_read_b128 v[206:209], v179 offset:6784
	s_waitcnt lgkmcnt(7)
	v_mfma_f32_16x16x32_bf16 v[96:99], v[210:213], v[12:15], v[24:27]
	v_mfma_f32_16x16x32_bf16 v[100:103], v[210:213], v[20:23], v[28:31]
	ds_read_b128 v[210:213], v179 offset:10112
	s_waitcnt lgkmcnt(7)
	v_mfma_f32_16x16x32_bf16 v[72:75], v[214:217], v[8:11], v[72:75]
	v_mfma_f32_16x16x32_bf16 v[76:79], v[214:217], v[16:19], v[76:79]
	ds_read_b128 v[214:217], v179 offset:13312
	s_waitcnt lgkmcnt(7)
	v_mfma_f32_16x16x32_bf16 v[80:83], v[218:221], v[8:11], v[80:83]
	v_mfma_f32_16x16x32_bf16 v[84:87], v[218:221], v[16:19], v[84:87]
	ds_read_b128 v[218:221], v179 offset:16640
	s_waitcnt lgkmcnt(7)
	v_mfma_f32_16x16x32_bf16 v[88:91], v[222:225], v[8:11], v[88:91]
	v_mfma_f32_16x16x32_bf16 v[92:95], v[222:225], v[16:19], v[92:95]
	ds_read_b128 v[222:225], v179 offset:19968
	s_waitcnt lgkmcnt(7)
	v_mfma_f32_16x16x32_bf16 v[96:99], v[226:229], v[8:11], v[96:99]
	v_mfma_f32_16x16x32_bf16 v[100:103], v[226:229], v[16:19], v[100:103]
	ds_read_b128 v[226:229], v179 offset:23296
	s_waitcnt lgkmcnt(7)
	v_mfma_f32_16x16x32_bf16 v[72:75], v[198:201], v[4:7], v[72:75]
	v_mfma_f32_16x16x32_bf16 v[76:79], v[198:201], v[0:3], v[76:79]
	ds_read_b128 v[198:201], v179 offset:13376
	s_waitcnt lgkmcnt(7)
	v_mfma_f32_16x16x32_bf16 v[80:83], v[202:205], v[4:7], v[80:83]
	v_mfma_f32_16x16x32_bf16 v[84:87], v[202:205], v[0:3], v[84:87]
	ds_read_b128 v[202:205], v179 offset:16704
	s_waitcnt lgkmcnt(7)
	v_mfma_f32_16x16x32_bf16 v[88:91], v[206:209], v[4:7], v[88:91]
	v_mfma_f32_16x16x32_bf16 v[92:95], v[206:209], v[0:3], v[92:95]
	ds_read_b128 v[206:209], v179 offset:20032
	s_waitcnt lgkmcnt(7)
	v_mfma_f32_16x16x32_bf16 v[96:99], v[210:213], v[4:7], v[96:99]
	v_mfma_f32_16x16x32_bf16 v[100:103], v[210:213], v[0:3], v[100:103]
	ds_read_b128 v[210:213], v179 offset:23360
	s_waitcnt lgkmcnt(7)
	v_mfma_f32_16x16x32_bf16 v[104:107], v[214:217], v[12:15], v[24:27]
	v_mfma_f32_16x16x32_bf16 v[108:111], v[214:217], v[20:23], v[28:31]
	ds_read_b128 v[214:217], v179 offset:13440
	s_waitcnt lgkmcnt(7)
	v_mfma_f32_16x16x32_bf16 v[112:115], v[218:221], v[12:15], v[24:27]
	v_mfma_f32_16x16x32_bf16 v[116:119], v[218:221], v[20:23], v[28:31]
	ds_read_b128 v[218:221], v179 offset:16768
	s_waitcnt lgkmcnt(7)
	v_mfma_f32_16x16x32_bf16 v[120:123], v[222:225], v[12:15], v[24:27]
	v_exp_f32_e32 v72, v72
	v_mfma_f32_16x16x32_bf16 v[124:127], v[222:225], v[20:23], v[28:31]
	v_exp_f32_e32 v73, v73
	ds_read_b128 v[222:225], v179 offset:20096
	s_waitcnt lgkmcnt(7)
	v_mfma_f32_16x16x32_bf16 v[128:131], v[226:229], v[12:15], v[24:27]
	v_exp_f32_e32 v74, v74
	v_mfma_f32_16x16x32_bf16 v[132:135], v[226:229], v[20:23], v[28:31]
	v_exp_f32_e32 v75, v75
	ds_read_b128 v[226:229], v179 offset:23424
	s_waitcnt lgkmcnt(7)
	v_mfma_f32_16x16x32_bf16 v[104:107], v[198:201], v[8:11], v[104:107]
	v_exp_f32_e32 v80, v80
	v_exp_f32_e32 v81, v81
	v_mfma_f32_16x16x32_bf16 v[108:111], v[198:201], v[16:19], v[108:111]
	v_exp_f32_e32 v82, v82
	s_waitcnt lgkmcnt(6)
	v_mfma_f32_16x16x32_bf16 v[112:115], v[202:205], v[8:11], v[112:115]
	v_exp_f32_e32 v83, v83
	v_mfma_f32_16x16x32_bf16 v[116:119], v[202:205], v[16:19], v[116:119]
	v_exp_f32_e32 v76, v76
	s_waitcnt lgkmcnt(5)
; DEV float ex2(float x) { return __builtin_amdgcn_exp2f(x); }
; DEV void attn_item(const Params& p, int bl, int head, int q0, int nkeys, char* smem, int tid) {
;     ...
;     for (int hh = 0; hh < 2; ++hh) {
;       f32x4 s[4][2];
; #pragma unroll
;       for (int kf = 0; kf < 4; ++kf) {
; #pragma unroll
;         for (int ks = 0; ks < 3; ++ks) {
;           bf16x8 a = *(const bf16x8*)(kb + (hh * 64 + kf * 16 + fr) * KROW + ks * 64 + fq * 16);
;           s[kf][0] = __builtin_amdgcn_mfma_f32_16x16x32_bf16(a, qf[0][ks], ks == 0 ? negm[0] : s[kf][0], 0, 0, 0);
;           s[kf][1] = __builtin_amdgcn_mfma_f32_16x16x32_bf16(a, qf[1][ks], ks == 0 ? negm[1] : s[kf][1], 0, 0, 0);
;         }
;       }
; #pragma unroll
;       for (int kk = 0; kk < 2; ++kk) {
;         bf16x8 pb[2];
; #pragma unroll
;         for (int qt = 0; qt < 2; ++qt) {
;           const float e0 = ex2(s[2 * kk][qt][0]), e1 = ex2(s[2 * kk][qt][1]), e2 = ex2(s[2 * kk][qt][2]), e3 = ex2(s[2 * kk][qt][3]);
;           const float e4 = ex2(s[2 * kk + 1][qt][0]), e5 = ex2(s[2 * kk + 1][qt][1]), e6 = ex2(s[2 * kk + 1][qt][2]), e7 = ex2(s[2 * kk + 1][qt][3]);
;           u32x4 cw = {pack2(e0, e1), pack2(e2, e3), pack2(e4, e5), pack2(e6, e7)};
;           pb[qt] = __builtin_bit_cast(bf16x8, cw);
;         }
;         lacc[0] = __builtin_amdgcn_mfma_f32_16x16x32_bf16(ones, pb[0], lacc[0], 0, 0, 0);
;         lacc[1] = __builtin_amdgcn_mfma_f32_16x16x32_bf16(ones, pb[1], lacc[1], 0, 0, 0);
; #pragma unroll
;         for (int dvf = 0; dvf < 4; ++dvf) {
;           const char* vp = vb + (dvf * 16 + fr) * VROW + (hh * 64 + kk * 32 + fq * 4) * 2;
;           const uint2 h0 = *(const uint2*)vp, h1 = *(const uint2*)(vp + 32);
;           u32x4 vw = {h0.x, h0.y, h1.x, h1.y};
;           const bf16x8 va = __builtin_bit_cast(bf16x8, vw);
;           o[dvf][0] = __builtin_amdgcn_mfma_f32_16x16x32_bf16(va, pb[0], o[dvf][0], 0, 0, 0);
;           o[dvf][1] = __builtin_amdgcn_mfma_f32_16x16x32_bf16(va, pb[1], o[dvf][1], 0, 0, 0);
;         }
;       }
;     }
;     if (t + 1 < nt) {
;       char* nb = smem + ((t + 1) & 1) * ASTG;
; #pragma unroll
;       for (int i = 0; i < 3; ++i) *(u32x4*)(nb + koff[i]) = kr[i];
; #pragma unroll
;       for (int i = 0; i < 2; ++i) *(u32x4*)(nb + KBYTES + voffl[i]) = vr[i];
;     }
	v_mfma_f32_16x16x32_bf16 v[120:123], v[206:209], v[8:11], v[120:123]
	v_exp_f32_e32 v77, v77
	v_mfma_f32_16x16x32_bf16 v[124:127], v[206:209], v[16:19], v[124:127]
	v_exp_f32_e32 v78, v78
	v_exp_f32_e32 v79, v79
	s_waitcnt lgkmcnt(4)
	v_mfma_f32_16x16x32_bf16 v[128:131], v[210:213], v[8:11], v[128:131]
	v_exp_f32_e32 v84, v84
	v_mfma_f32_16x16x32_bf16 v[132:135], v[210:213], v[16:19], v[132:135]
	v_exp_f32_e32 v85, v85
	s_waitcnt lgkmcnt(3)
	v_mfma_f32_16x16x32_bf16 v[104:107], v[214:217], v[4:7], v[104:107]
	v_exp_f32_e32 v86, v86
	v_mfma_f32_16x16x32_bf16 v[108:111], v[214:217], v[0:3], v[108:111]
	v_exp_f32_e32 v87, v87
	s_waitcnt lgkmcnt(2)
	v_mfma_f32_16x16x32_bf16 v[112:115], v[218:221], v[4:7], v[112:115]
	v_cvt_pk_bf16_f32 v136, v72, v73
	v_cvt_pk_bf16_f32 v137, v74, v75
	v_mfma_f32_16x16x32_bf16 v[116:119], v[218:221], v[0:3], v[116:119]
	v_cvt_pk_bf16_f32 v138, v80, v81
	s_waitcnt lgkmcnt(1)
	v_mfma_f32_16x16x32_bf16 v[120:123], v[222:225], v[4:7], v[120:123]
	v_cvt_pk_bf16_f32 v139, v82, v83
	v_mfma_f32_16x16x32_bf16 v[124:127], v[222:225], v[0:3], v[124:127]
	v_cvt_pk_bf16_f32 v140, v76, v77
	s_waitcnt lgkmcnt(0)
	v_mfma_f32_16x16x32_bf16 v[128:131], v[226:229], v[4:7], v[128:131]
	v_cvt_pk_bf16_f32 v141, v78, v79
	v_mfma_f32_16x16x32_bf16 v[132:135], v[226:229], v[0:3], v[132:135]
	v_cvt_pk_bf16_f32 v142, v84, v85
	v_cvt_pk_bf16_f32 v143, v86, v87
	s_waitcnt vmcnt(0)
	ds_write_b128 v184, v[238:241]
	ds_write_b128 v185, v[242:245]
	ds_write_b128 v186, v[246:249]
	ds_write_b128 v187, v[230:233] offset:28672
	ds_write_b128 v188, v[234:237] offset:28672
	v_add3_u32 v180, s12, v176, v177
	ds_read_b64 v[198:199], v180 offset:26624
	ds_read_b64 v[200:201], v180 offset:26656
	ds_read_b64 v[202:203], v180 offset:30976
	ds_read_b64 v[204:205], v180 offset:31008
	ds_read_b64 v[206:207], v180 offset:35328
	ds_read_b64 v[208:209], v180 offset:35360
	ds_read_b64 v[210:211], v180 offset:39680
	ds_read_b64 v[212:213], v180 offset:39712
	ds_read_b64 v[214:215], v180 offset:26688
	ds_read_b64 v[216:217], v180 offset:26720
	ds_read_b64 v[218:219], v180 offset:31040
	ds_read_b64 v[220:221], v180 offset:31072
	ds_read_b64 v[222:223], v180 offset:35392
	ds_read_b64 v[224:225], v180 offset:35424
	ds_read_b64 v[226:227], v180 offset:39744
	ds_read_b64 v[228:229], v180 offset:39776
	v_mfma_f32_16x16x32_bf16 v[68:71], v[152:155], v[136:139], v[68:71]
	v_exp_f32_e32 v88, v88
	v_exp_f32_e32 v89, v89
	v_mfma_f32_16x16x32_bf16 v[56:59], v[152:155], v[140:143], v[56:59]
	v_exp_f32_e32 v90, v90
	v_exp_f32_e32 v91, v91
	s_waitcnt lgkmcnt(8)
	v_mfma_f32_16x16x32_bf16 v[32:35], v[198:201], v[136:139], v[32:35]
	v_exp_f32_e32 v96, v96
	v_exp_f32_e32 v97, v97
	v_mfma_f32_16x16x32_bf16 v[36:39], v[198:201], v[140:143], v[36:39]
	v_exp_f32_e32 v98, v98
	v_exp_f32_e32 v99, v99
	v_exp_f32_e32 v92, v92
	v_mfma_f32_16x16x32_bf16 v[40:43], v[202:205], v[136:139], v[40:43]
	v_exp_f32_e32 v93, v93
	v_exp_f32_e32 v94, v94
	v_mfma_f32_16x16x32_bf16 v[60:63], v[202:205], v[140:143], v[60:63]
	v_exp_f32_e32 v95, v95
	v_exp_f32_e32 v100, v100
	v_exp_f32_e32 v101, v101
	v_mfma_f32_16x16x32_bf16 v[44:47], v[206:209], v[136:139], v[44:47]
	v_exp_f32_e32 v102, v102
	v_exp_f32_e32 v103, v103
	v_mfma_f32_16x16x32_bf16 v[64:67], v[206:209], v[140:143], v[64:67]
	v_cvt_pk_bf16_f32 v144, v88, v89
	v_cvt_pk_bf16_f32 v145, v90, v91
	v_cvt_pk_bf16_f32 v146, v96, v97
	v_mfma_f32_16x16x32_bf16 v[48:51], v[210:213], v[136:139], v[48:51]
	v_cvt_pk_bf16_f32 v147, v98, v99
	v_cvt_pk_bf16_f32 v148, v92, v93
	v_mfma_f32_16x16x32_bf16 v[52:55], v[210:213], v[140:143], v[52:55]
	v_cvt_pk_bf16_f32 v149, v94, v95
	v_cvt_pk_bf16_f32 v150, v100, v101
	v_cvt_pk_bf16_f32 v151, v102, v103
	ds_read_b64 v[198:199], v180 offset:26752
	ds_read_b64 v[200:201], v180 offset:26784
	ds_read_b64 v[202:203], v180 offset:31104
	ds_read_b64 v[204:205], v180 offset:31136
	ds_read_b64 v[206:207], v180 offset:35456
	ds_read_b64 v[208:209], v180 offset:35488
	ds_read_b64 v[210:211], v180 offset:39808
	ds_read_b64 v[212:213], v180 offset:39840
	s_nop 1
	v_mfma_f32_16x16x32_bf16 v[68:71], v[152:155], v[144:147], v[68:71]
	v_exp_f32_e32 v104, v104
	v_exp_f32_e32 v105, v105
	v_mfma_f32_16x16x32_bf16 v[56:59], v[152:155], v[148:151], v[56:59]
	v_exp_f32_e32 v106, v106
	v_exp_f32_e32 v107, v107
	s_waitcnt lgkmcnt(8)
	v_mfma_f32_16x16x32_bf16 v[32:35], v[214:217], v[144:147], v[32:35]
	v_exp_f32_e32 v112, v112
	v_exp_f32_e32 v113, v113
	v_mfma_f32_16x16x32_bf16 v[36:39], v[214:217], v[148:151], v[36:39]
	v_exp_f32_e32 v114, v114
	v_exp_f32_e32 v115, v115
	v_exp_f32_e32 v108, v108
	v_mfma_f32_16x16x32_bf16 v[40:43], v[218:221], v[144:147], v[40:43]
	v_exp_f32_e32 v109, v109
	v_exp_f32_e32 v110, v110
	v_mfma_f32_16x16x32_bf16 v[60:63], v[218:221], v[148:151], v[60:63]
	v_exp_f32_e32 v111, v111
	v_exp_f32_e32 v116, v116
	v_exp_f32_e32 v117, v117
	v_mfma_f32_16x16x32_bf16 v[44:47], v[222:225], v[144:147], v[44:47]
	v_exp_f32_e32 v118, v118
	v_exp_f32_e32 v119, v119
	v_mfma_f32_16x16x32_bf16 v[64:67], v[222:225], v[148:151], v[64:67]
	v_cvt_pk_bf16_f32 v136, v104, v105
	v_cvt_pk_bf16_f32 v137, v106, v107
	v_cvt_pk_bf16_f32 v138, v112, v113
	v_mfma_f32_16x16x32_bf16 v[48:51], v[226:229], v[144:147], v[48:51]
	v_cvt_pk_bf16_f32 v139, v114, v115
	v_cvt_pk_bf16_f32 v140, v108, v109
	v_mfma_f32_16x16x32_bf16 v[52:55], v[226:229], v[148:151], v[52:55]
	v_cvt_pk_bf16_f32 v141, v110, v111
	v_cvt_pk_bf16_f32 v142, v116, v117
	v_cvt_pk_bf16_f32 v143, v118, v119
	ds_read_b64 v[214:215], v180 offset:26816
	ds_read_b64 v[216:217], v180 offset:26848
	ds_read_b64 v[218:219], v180 offset:31168
	ds_read_b64 v[220:221], v180 offset:31200
	ds_read_b64 v[222:223], v180 offset:35520
	ds_read_b64 v[224:225], v180 offset:35552
	ds_read_b64 v[226:227], v180 offset:39872
	ds_read_b64 v[228:229], v180 offset:39904
	s_nop 1
	v_mfma_f32_16x16x32_bf16 v[68:71], v[152:155], v[136:139], v[68:71]
	v_exp_f32_e32 v120, v120
	v_exp_f32_e32 v121, v121
	v_mfma_f32_16x16x32_bf16 v[56:59], v[152:155], v[140:143], v[56:59]
	v_exp_f32_e32 v122, v122
	v_exp_f32_e32 v123, v123
	s_waitcnt lgkmcnt(8)
; DEV void attn_item(const Params& p, int bl, int head, int q0, int nkeys, char* smem, int tid) {
;     ...
;   for (int t = 0; t < nt; ++t) {
;     if (t + 1 < nt) {
; #pragma unroll
;       for (int i = 0; i < 3; ++i) kr[i] = *(const u32x4*)(Kg + (long)(t + 1) * 128 * 96 + (long)(i * 512 + tid) * 8);
; #pragma unroll
;       for (int i = 0; i < 2; ++i) vr[i] = *(const u32x4*)(Vg + (t + 1) * 128 + voffg[i]);
;     }
;     const char* kb = smem + (t & 1) * ASTG;
;     const char* vb = kb + KBYTES;
; #pragma unroll
;     for (int hh = 0; hh < 2; ++hh) {
;       f32x4 s[4][2];
; #pragma unroll
;       for (int kf = 0; kf < 4; ++kf) {
; #pragma unroll
;         for (int ks = 0; ks < 3; ++ks) {
;           bf16x8 a = *(const bf16x8*)(kb + (hh * 64 + kf * 16 + fr) * KROW + ks * 64 + fq * 16);
;           s[kf][0] = __builtin_amdgcn_mfma_f32_16x16x32_bf16(a, qf[0][ks], ks == 0 ? negm[0] : s[kf][0], 0, 0, 0);
;           s[kf][1] = __builtin_amdgcn_mfma_f32_16x16x32_bf16(a, qf[1][ks], ks == 0 ? negm[1] : s[kf][1], 0, 0, 0);
;         }
;       }
; #pragma unroll
;       for (int kk = 0; kk < 2; ++kk) {
;         bf16x8 pb[2];
; #pragma unroll
;         for (int qt = 0; qt < 2; ++qt) {
;           const float e0 = ex2(s[2 * kk][qt][0]), e1 = ex2(s[2 * kk][qt][1]), e2 = ex2(s[2 * kk][qt][2]), e3 = ex2(s[2 * kk][qt][3]);
;           const float e4 = ex2(s[2 * kk + 1][qt][0]), e5 = ex2(s[2 * kk + 1][qt][1]), e6 = ex2(s[2 * kk + 1][qt][2]), e7 = ex2(s[2 * kk + 1][qt][3]);
;           u32x4 cw = {pack2(e0, e1), pack2(e2, e3), pack2(e4, e5), pack2(e6, e7)};
;           pb[qt] = __builtin_bit_cast(bf16x8, cw);
;         }
;         lacc[0] = __builtin_amdgcn_mfma_f32_16x16x32_bf16(ones, pb[0], lacc[0], 0, 0, 0);
;         lacc[1] = __builtin_amdgcn_mfma_f32_16x16x32_bf16(ones, pb[1], lacc[1], 0, 0, 0);
; #pragma unroll
;         for (int dvf = 0; dvf < 4; ++dvf) {
;           const char* vp = vb + (dvf * 16 + fr) * VROW + (hh * 64 + kk * 32 + fq * 4) * 2;
;           const uint2 h0 = *(const uint2*)vp, h1 = *(const uint2*)(vp + 32);
;           u32x4 vw = {h0.x, h0.y, h1.x, h1.y};
;           const bf16x8 va = __builtin_bit_cast(bf16x8, vw);
;           o[dvf][0] = __builtin_amdgcn_mfma_f32_16x16x32_bf16(va, pb[0], o[dvf][0], 0, 0, 0);
;           o[dvf][1] = __builtin_amdgcn_mfma_f32_16x16x32_bf16(va, pb[1], o[dvf][1], 0, 0, 0);
;         }
;       }
;     }
	v_mfma_f32_16x16x32_bf16 v[32:35], v[198:201], v[136:139], v[32:35]
	v_exp_f32_e32 v128, v128
	v_exp_f32_e32 v129, v129
	v_mfma_f32_16x16x32_bf16 v[36:39], v[198:201], v[140:143], v[36:39]
	v_exp_f32_e32 v130, v130
	v_exp_f32_e32 v131, v131
	v_exp_f32_e32 v124, v124
	v_mfma_f32_16x16x32_bf16 v[40:43], v[202:205], v[136:139], v[40:43]
	v_exp_f32_e32 v125, v125
	v_exp_f32_e32 v126, v126
	v_mfma_f32_16x16x32_bf16 v[60:63], v[202:205], v[140:143], v[60:63]
	v_exp_f32_e32 v127, v127
	v_exp_f32_e32 v132, v132
	v_exp_f32_e32 v133, v133
	v_mfma_f32_16x16x32_bf16 v[44:47], v[206:209], v[136:139], v[44:47]
	v_exp_f32_e32 v134, v134
	v_exp_f32_e32 v135, v135
	v_mfma_f32_16x16x32_bf16 v[64:67], v[206:209], v[140:143], v[64:67]
	v_cvt_pk_bf16_f32 v144, v120, v121
	v_cvt_pk_bf16_f32 v145, v122, v123
	v_cvt_pk_bf16_f32 v146, v128, v129
	v_mfma_f32_16x16x32_bf16 v[48:51], v[210:213], v[136:139], v[48:51]
	v_cvt_pk_bf16_f32 v147, v130, v131
	v_cvt_pk_bf16_f32 v148, v124, v125
	v_mfma_f32_16x16x32_bf16 v[52:55], v[210:213], v[140:143], v[52:55]
	v_cvt_pk_bf16_f32 v149, v126, v127
	v_cvt_pk_bf16_f32 v150, v132, v133
	v_cvt_pk_bf16_f32 v151, v134, v135
	s_nop 1
	v_mfma_f32_16x16x32_bf16 v[68:71], v[152:155], v[144:147], v[68:71]
	v_mfma_f32_16x16x32_bf16 v[56:59], v[152:155], v[148:151], v[56:59]
	s_waitcnt lgkmcnt(0)
	v_mfma_f32_16x16x32_bf16 v[32:35], v[214:217], v[144:147], v[32:35]
	v_mfma_f32_16x16x32_bf16 v[36:39], v[214:217], v[148:151], v[36:39]
	v_mfma_f32_16x16x32_bf16 v[40:43], v[218:221], v[144:147], v[40:43]
	v_mfma_f32_16x16x32_bf16 v[60:63], v[218:221], v[148:151], v[60:63]
	v_mfma_f32_16x16x32_bf16 v[44:47], v[222:225], v[144:147], v[44:47]
	v_mfma_f32_16x16x32_bf16 v[64:67], v[222:225], v[148:151], v[64:67]
	v_mfma_f32_16x16x32_bf16 v[48:51], v[226:229], v[144:147], v[48:51]
	v_mfma_f32_16x16x32_bf16 v[52:55], v[226:229], v[148:151], v[52:55]
	s_waitcnt lgkmcnt(0)
	s_barrier
	s_mov_b32 s18, s15
	s_mov_b32 s15, s12
	s_mov_b32 s12, s9
	s_mov_b32 s9, s18
	s_add_i32 s13, s13, 1
.Lattn_a_loop:
	global_load_dwordx4 v[230:233], v[164:165], off
	global_load_dwordx4 v[234:237], v[166:167], off
	global_load_dwordx4 v[238:241], v[168:169], off
	global_load_dwordx4 v[242:245], v[170:171], off
	global_load_dwordx4 v[246:249], v[172:173], off
	v_lshl_add_u64 v[164:165], v[164:165], 0, s[26:27]
	v_lshl_add_u64 v[166:167], v[166:167], 0, s[26:27]
	v_lshl_add_u64 v[168:169], v[168:169], 0, s[16:17]
	v_lshl_add_u64 v[170:171], v[170:171], 0, s[16:17]
	v_lshl_add_u64 v[172:173], v[172:173], 0, s[16:17]
	v_add_u32_e32 v184, s9, v190
	v_add_u32_e32 v185, s9, v191
	v_add_u32_e32 v186, s9, v192
	v_add_u32_e32 v187, s9, v160
	v_add_u32_e32 v188, s9, v162
	v_add3_u32 v179, s12, v156, v181
	ds_read_b128 v[198:201], v179
	ds_read_b128 v[202:205], v179 offset:3584
	ds_read_b128 v[206:209], v179 offset:7168
	ds_read_b128 v[210:213], v179 offset:10752
	ds_read_b128 v[214:217], v179 offset:64
	ds_read_b128 v[218:221], v179 offset:3648
	ds_read_b128 v[222:225], v179 offset:7232
	ds_read_b128 v[226:229], v179 offset:10816
	s_waitcnt lgkmcnt(7)
	v_mfma_f32_16x16x32_bf16 v[72:75], v[198:201], v[12:15], v[24:27]
	v_mfma_f32_16x16x32_bf16 v[76:79], v[198:201], v[20:23], v[28:31]
	ds_read_b128 v[198:201], v179 offset:128
	s_waitcnt lgkmcnt(7)
	v_mfma_f32_16x16x32_bf16 v[80:83], v[202:205], v[12:15], v[24:27]
	v_mfma_f32_16x16x32_bf16 v[84:87], v[202:205], v[20:23], v[28:31]
	ds_read_b128 v[202:205], v179 offset:3712
	s_waitcnt lgkmcnt(7)
	v_mfma_f32_16x16x32_bf16 v[88:91], v[206:209], v[12:15], v[24:27]
	v_mfma_f32_16x16x32_bf16 v[92:95], v[206:209], v[20:23], v[28:31]
	ds_read_b128 v[206:209], v179 offset:7296
	s_waitcnt lgkmcnt(7)
	v_mfma_f32_16x16x32_bf16 v[96:99], v[210:213], v[12:15], v[24:27]
	v_mfma_f32_16x16x32_bf16 v[100:103], v[210:213], v[20:23], v[28:31]
	ds_read_b128 v[210:213], v179 offset:10880
	s_waitcnt lgkmcnt(7)
	v_mfma_f32_16x16x32_bf16 v[72:75], v[214:217], v[8:11], v[72:75]
	v_mfma_f32_16x16x32_bf16 v[76:79], v[214:217], v[16:19], v[76:79]
	ds_read_b128 v[214:217], v179 offset:14336
	s_waitcnt lgkmcnt(7)
	v_mfma_f32_16x16x32_bf16 v[80:83], v[218:221], v[8:11], v[80:83]
	v_mfma_f32_16x16x32_bf16 v[84:87], v[218:221], v[16:19], v[84:87]
	ds_read_b128 v[218:221], v179 offset:17920
	s_waitcnt lgkmcnt(7)
	v_mfma_f32_16x16x32_bf16 v[88:91], v[222:225], v[8:11], v[88:91]
	v_mfma_f32_16x16x32_bf16 v[92:95], v[222:225], v[16:19], v[92:95]
	ds_read_b128 v[222:225], v179 offset:21504
	s_waitcnt lgkmcnt(7)
	v_mfma_f32_16x16x32_bf16 v[96:99], v[226:229], v[8:11], v[96:99]
	v_mfma_f32_16x16x32_bf16 v[100:103], v[226:229], v[16:19], v[100:103]
	ds_read_b128 v[226:229], v179 offset:25088
	s_waitcnt lgkmcnt(7)
	v_mfma_f32_16x16x32_bf16 v[72:75], v[198:201], v[4:7], v[72:75]
	v_mfma_f32_16x16x32_bf16 v[76:79], v[198:201], v[0:3], v[76:79]
	ds_read_b128 v[198:201], v179 offset:14400
	s_waitcnt lgkmcnt(7)
	v_mfma_f32_16x16x32_bf16 v[80:83], v[202:205], v[4:7], v[80:83]
	v_mfma_f32_16x16x32_bf16 v[84:87], v[202:205], v[0:3], v[84:87]
	ds_read_b128 v[202:205], v179 offset:17984
	s_waitcnt lgkmcnt(7)
	v_mfma_f32_16x16x32_bf16 v[88:91], v[206:209], v[4:7], v[88:91]
	v_mfma_f32_16x16x32_bf16 v[92:95], v[206:209], v[0:3], v[92:95]
	ds_read_b128 v[206:209], v179 offset:21568
	s_waitcnt lgkmcnt(7)
	v_mfma_f32_16x16x32_bf16 v[96:99], v[210:213], v[4:7], v[96:99]
	v_mfma_f32_16x16x32_bf16 v[100:103], v[210:213], v[0:3], v[100:103]
	ds_read_b128 v[210:213], v179 offset:25152
	s_waitcnt lgkmcnt(7)
	v_mfma_f32_16x16x32_bf16 v[104:107], v[214:217], v[12:15], v[24:27]
	v_mfma_f32_16x16x32_bf16 v[108:111], v[214:217], v[20:23], v[28:31]
	ds_read_b128 v[214:217], v179 offset:14464
	s_waitcnt lgkmcnt(7)
; DEV float ex2(float x) { return __builtin_amdgcn_exp2f(x); }
; DEV void attn_item(const Params& p, int bl, int head, int q0, int nkeys, char* smem, int tid) {
;     ...
;     for (int hh = 0; hh < 2; ++hh) {
;       f32x4 s[4][2];
; #pragma unroll
;       for (int kf = 0; kf < 4; ++kf) {
; #pragma unroll
;         for (int ks = 0; ks < 3; ++ks) {
;           bf16x8 a = *(const bf16x8*)(kb + (hh * 64 + kf * 16 + fr) * KROW + ks * 64 + fq * 16);
;           s[kf][0] = __builtin_amdgcn_mfma_f32_16x16x32_bf16(a, qf[0][ks], ks == 0 ? negm[0] : s[kf][0], 0, 0, 0);
;           s[kf][1] = __builtin_amdgcn_mfma_f32_16x16x32_bf16(a, qf[1][ks], ks == 0 ? negm[1] : s[kf][1], 0, 0, 0);
;         }
;       }
; #pragma unroll
;       for (int kk = 0; kk < 2; ++kk) {
;         bf16x8 pb[2];
; #pragma unroll
;         for (int qt = 0; qt < 2; ++qt) {
;           const float e0 = ex2(s[2 * kk][qt][0]), e1 = ex2(s[2 * kk][qt][1]), e2 = ex2(s[2 * kk][qt][2]), e3 = ex2(s[2 * kk][qt][3]);
;           const float e4 = ex2(s[2 * kk + 1][qt][0]), e5 = ex2(s[2 * kk + 1][qt][1]), e6 = ex2(s[2 * kk + 1][qt][2]), e7 = ex2(s[2 * kk + 1][qt][3]);
;           u32x4 cw = {pack2(e0, e1), pack2(e2, e3), pack2(e4, e5), pack2(e6, e7)};
;           pb[qt] = __builtin_bit_cast(bf16x8, cw);
;         }
;         lacc[0] = __builtin_amdgcn_mfma_f32_16x16x32_bf16(ones, pb[0], lacc[0], 0, 0, 0);
;         lacc[1] = __builtin_amdgcn_mfma_f32_16x16x32_bf16(ones, pb[1], lacc[1], 0, 0, 0);
; #pragma unroll
;         for (int dvf = 0; dvf < 4; ++dvf) {
;           const char* vp = vb + (dvf * 16 + fr) * VROW + (hh * 64 + kk * 32 + fq * 4) * 2;
;           const uint2 h0 = *(const uint2*)vp, h1 = *(const uint2*)(vp + 32);
;           u32x4 vw = {h0.x, h0.y, h1.x, h1.y};
;           const bf16x8 va = __builtin_bit_cast(bf16x8, vw);
;           o[dvf][0] = __builtin_amdgcn_mfma_f32_16x16x32_bf16(va, pb[0], o[dvf][0], 0, 0, 0);
;           o[dvf][1] = __builtin_amdgcn_mfma_f32_16x16x32_bf16(va, pb[1], o[dvf][1], 0, 0, 0);
;         }
;       }
;     }
;     if (t + 1 < nt) {
;       char* nb = smem + ((t + 1) & 1) * ASTG;
; #pragma unroll
;       for (int i = 0; i < 3; ++i) *(u32x4*)(nb + koff[i]) = kr[i];
; #pragma unroll
;       for (int i = 0; i < 2; ++i) *(u32x4*)(nb + KBYTES + voffl[i]) = vr[i];
;     }
	v_mfma_f32_16x16x32_bf16 v[112:115], v[218:221], v[12:15], v[24:27]
	v_mfma_f32_16x16x32_bf16 v[116:119], v[218:221], v[20:23], v[28:31]
	ds_read_b128 v[218:221], v179 offset:18048
	s_waitcnt lgkmcnt(7)
	v_mfma_f32_16x16x32_bf16 v[120:123], v[222:225], v[12:15], v[24:27]
	v_exp_f32_e32 v72, v72
	v_mfma_f32_16x16x32_bf16 v[124:127], v[222:225], v[20:23], v[28:31]
	v_exp_f32_e32 v73, v73
	ds_read_b128 v[222:225], v179 offset:21632
	s_waitcnt lgkmcnt(7)
	v_mfma_f32_16x16x32_bf16 v[128:131], v[226:229], v[12:15], v[24:27]
	v_exp_f32_e32 v74, v74
	v_mfma_f32_16x16x32_bf16 v[132:135], v[226:229], v[20:23], v[28:31]
	v_exp_f32_e32 v75, v75
	ds_read_b128 v[226:229], v179 offset:25216
	s_waitcnt lgkmcnt(7)
	v_mfma_f32_16x16x32_bf16 v[104:107], v[198:201], v[8:11], v[104:107]
	v_exp_f32_e32 v80, v80
	v_exp_f32_e32 v81, v81
	v_mfma_f32_16x16x32_bf16 v[108:111], v[198:201], v[16:19], v[108:111]
	v_exp_f32_e32 v82, v82
	s_waitcnt lgkmcnt(6)
	v_mfma_f32_16x16x32_bf16 v[112:115], v[202:205], v[8:11], v[112:115]
	v_exp_f32_e32 v83, v83
	v_mfma_f32_16x16x32_bf16 v[116:119], v[202:205], v[16:19], v[116:119]
	v_exp_f32_e32 v76, v76
	s_waitcnt lgkmcnt(5)
	v_mfma_f32_16x16x32_bf16 v[120:123], v[206:209], v[8:11], v[120:123]
	v_exp_f32_e32 v77, v77
	v_mfma_f32_16x16x32_bf16 v[124:127], v[206:209], v[16:19], v[124:127]
	v_exp_f32_e32 v78, v78
	v_exp_f32_e32 v79, v79
	s_waitcnt lgkmcnt(4)
	v_mfma_f32_16x16x32_bf16 v[128:131], v[210:213], v[8:11], v[128:131]
	v_exp_f32_e32 v84, v84
	v_mfma_f32_16x16x32_bf16 v[132:135], v[210:213], v[16:19], v[132:135]
	v_exp_f32_e32 v85, v85
	s_waitcnt lgkmcnt(3)
	v_mfma_f32_16x16x32_bf16 v[104:107], v[214:217], v[4:7], v[104:107]
	v_exp_f32_e32 v86, v86
	v_mfma_f32_16x16x32_bf16 v[108:111], v[214:217], v[0:3], v[108:111]
	v_exp_f32_e32 v87, v87
	s_waitcnt lgkmcnt(2)
	v_mfma_f32_16x16x32_bf16 v[112:115], v[218:221], v[4:7], v[112:115]
	v_cvt_pk_bf16_f32 v136, v72, v73
	v_cvt_pk_bf16_f32 v137, v74, v75
	v_mfma_f32_16x16x32_bf16 v[116:119], v[218:221], v[0:3], v[116:119]
	v_cvt_pk_bf16_f32 v138, v80, v81
	s_waitcnt lgkmcnt(1)
	v_mfma_f32_16x16x32_bf16 v[120:123], v[222:225], v[4:7], v[120:123]
	v_cvt_pk_bf16_f32 v139, v82, v83
	v_mfma_f32_16x16x32_bf16 v[124:127], v[222:225], v[0:3], v[124:127]
	v_cvt_pk_bf16_f32 v140, v76, v77
	s_waitcnt lgkmcnt(0)
	v_mfma_f32_16x16x32_bf16 v[128:131], v[226:229], v[4:7], v[128:131]
	v_cvt_pk_bf16_f32 v141, v78, v79
	v_mfma_f32_16x16x32_bf16 v[132:135], v[226:229], v[0:3], v[132:135]
	v_cvt_pk_bf16_f32 v142, v84, v85
	v_cvt_pk_bf16_f32 v143, v86, v87
	s_waitcnt vmcnt(0)
	ds_write_b128 v184, v[238:241]
	ds_write_b128 v185, v[242:245]
	ds_write_b128 v186, v[246:249]
	ds_write_b128 v187, v[230:233] offset:28672
	ds_write_b128 v188, v[234:237] offset:28672
	v_add3_u32 v180, s12, v176, v177
	ds_read_b64 v[198:199], v180 offset:28672
	ds_read_b64 v[200:201], v180 offset:28704
	ds_read_b64 v[202:203], v180 offset:33024
	ds_read_b64 v[204:205], v180 offset:33056
	ds_read_b64 v[206:207], v180 offset:37376
	ds_read_b64 v[208:209], v180 offset:37408
	ds_read_b64 v[210:211], v180 offset:41728
	ds_read_b64 v[212:213], v180 offset:41760
	ds_read_b64 v[214:215], v180 offset:28736
	ds_read_b64 v[216:217], v180 offset:28768
	ds_read_b64 v[218:219], v180 offset:33088
	ds_read_b64 v[220:221], v180 offset:33120
	ds_read_b64 v[222:223], v180 offset:37440
	ds_read_b64 v[224:225], v180 offset:37472
	ds_read_b64 v[226:227], v180 offset:41792
	ds_read_b64 v[228:229], v180 offset:41824
	v_mfma_f32_16x16x32_bf16 v[68:71], v[152:155], v[136:139], v[68:71]
	v_exp_f32_e32 v88, v88
	v_exp_f32_e32 v89, v89
	v_mfma_f32_16x16x32_bf16 v[56:59], v[152:155], v[140:143], v[56:59]
	v_exp_f32_e32 v90, v90
	v_exp_f32_e32 v91, v91
	s_waitcnt lgkmcnt(8)
	v_mfma_f32_16x16x32_bf16 v[32:35], v[198:201], v[136:139], v[32:35]
	v_exp_f32_e32 v96, v96
	v_exp_f32_e32 v97, v97
	v_mfma_f32_16x16x32_bf16 v[36:39], v[198:201], v[140:143], v[36:39]
	v_exp_f32_e32 v98, v98
	v_exp_f32_e32 v99, v99
	v_exp_f32_e32 v92, v92
	v_mfma_f32_16x16x32_bf16 v[40:43], v[202:205], v[136:139], v[40:43]
	v_exp_f32_e32 v93, v93
	v_exp_f32_e32 v94, v94
	v_mfma_f32_16x16x32_bf16 v[60:63], v[202:205], v[140:143], v[60:63]
	v_exp_f32_e32 v95, v95
	v_exp_f32_e32 v100, v100
	v_exp_f32_e32 v101, v101
	v_mfma_f32_16x16x32_bf16 v[44:47], v[206:209], v[136:139], v[44:47]
	v_exp_f32_e32 v102, v102
	v_exp_f32_e32 v103, v103
	v_mfma_f32_16x16x32_bf16 v[64:67], v[206:209], v[140:143], v[64:67]
	v_cvt_pk_bf16_f32 v144, v88, v89
	v_cvt_pk_bf16_f32 v145, v90, v91
	v_cvt_pk_bf16_f32 v146, v96, v97
	v_mfma_f32_16x16x32_bf16 v[48:51], v[210:213], v[136:139], v[48:51]
	v_cvt_pk_bf16_f32 v147, v98, v99
	v_cvt_pk_bf16_f32 v148, v92, v93
	v_mfma_f32_16x16x32_bf16 v[52:55], v[210:213], v[140:143], v[52:55]
	v_cvt_pk_bf16_f32 v149, v94, v95
	v_cvt_pk_bf16_f32 v150, v100, v101
	v_cvt_pk_bf16_f32 v151, v102, v103
	ds_read_b64 v[198:199], v180 offset:28800
	ds_read_b64 v[200:201], v180 offset:28832
	ds_read_b64 v[202:203], v180 offset:33152
	ds_read_b64 v[204:205], v180 offset:33184
	ds_read_b64 v[206:207], v180 offset:37504
	ds_read_b64 v[208:209], v180 offset:37536
	ds_read_b64 v[210:211], v180 offset:41856
	ds_read_b64 v[212:213], v180 offset:41888
	s_nop 1
	v_mfma_f32_16x16x32_bf16 v[68:71], v[152:155], v[144:147], v[68:71]
	v_exp_f32_e32 v104, v104
	v_exp_f32_e32 v105, v105
	v_mfma_f32_16x16x32_bf16 v[56:59], v[152:155], v[148:151], v[56:59]
	v_exp_f32_e32 v106, v106
	v_exp_f32_e32 v107, v107
	s_waitcnt lgkmcnt(8)
; DEV void attn_item(const Params& p, int bl, int head, int q0, int nkeys, char* smem, int tid) {
;     ...
;   for (int t = 0; t < nt; ++t) {
;     if (t + 1 < nt) {
; #pragma unroll
;       for (int i = 0; i < 3; ++i) kr[i] = *(const u32x4*)(Kg + (long)(t + 1) * 128 * 96 + (long)(i * 512 + tid) * 8);
; #pragma unroll
;       for (int i = 0; i < 2; ++i) vr[i] = *(const u32x4*)(Vg + (t + 1) * 128 + voffg[i]);
;     }
;     const char* kb = smem + (t & 1) * ASTG;
;     const char* vb = kb + KBYTES;
; #pragma unroll
;     for (int hh = 0; hh < 2; ++hh) {
;       f32x4 s[4][2];
; #pragma unroll
;       for (int kf = 0; kf < 4; ++kf) {
; #pragma unroll
;         for (int ks = 0; ks < 3; ++ks) {
;           bf16x8 a = *(const bf16x8*)(kb + (hh * 64 + kf * 16 + fr) * KROW + ks * 64 + fq * 16);
;           s[kf][0] = __builtin_amdgcn_mfma_f32_16x16x32_bf16(a, qf[0][ks], ks == 0 ? negm[0] : s[kf][0], 0, 0, 0);
;           s[kf][1] = __builtin_amdgcn_mfma_f32_16x16x32_bf16(a, qf[1][ks], ks == 0 ? negm[1] : s[kf][1], 0, 0, 0);
;         }
;       }
; #pragma unroll
;       for (int kk = 0; kk < 2; ++kk) {
;         bf16x8 pb[2];
; #pragma unroll
;         for (int qt = 0; qt < 2; ++qt) {
;           const float e0 = ex2(s[2 * kk][qt][0]), e1 = ex2(s[2 * kk][qt][1]), e2 = ex2(s[2 * kk][qt][2]), e3 = ex2(s[2 * kk][qt][3]);
;           const float e4 = ex2(s[2 * kk + 1][qt][0]), e5 = ex2(s[2 * kk + 1][qt][1]), e6 = ex2(s[2 * kk + 1][qt][2]), e7 = ex2(s[2 * kk + 1][qt][3]);
;           u32x4 cw = {pack2(e0, e1), pack2(e2, e3), pack2(e4, e5), pack2(e6, e7)};
;           pb[qt] = __builtin_bit_cast(bf16x8, cw);
;         }
;         lacc[0] = __builtin_amdgcn_mfma_f32_16x16x32_bf16(ones, pb[0], lacc[0], 0, 0, 0);
;         lacc[1] = __builtin_amdgcn_mfma_f32_16x16x32_bf16(ones, pb[1], lacc[1], 0, 0, 0);
; #pragma unroll
;         for (int dvf = 0; dvf < 4; ++dvf) {
;           const char* vp = vb + (dvf * 16 + fr) * VROW + (hh * 64 + kk * 32 + fq * 4) * 2;
;           const uint2 h0 = *(const uint2*)vp, h1 = *(const uint2*)(vp + 32);
;           u32x4 vw = {h0.x, h0.y, h1.x, h1.y};
;           const bf16x8 va = __builtin_bit_cast(bf16x8, vw);
;           o[dvf][0] = __builtin_amdgcn_mfma_f32_16x16x32_bf16(va, pb[0], o[dvf][0], 0, 0, 0);
;           o[dvf][1] = __builtin_amdgcn_mfma_f32_16x16x32_bf16(va, pb[1], o[dvf][1], 0, 0, 0);
;         }
;       }
;     }
	v_mfma_f32_16x16x32_bf16 v[32:35], v[214:217], v[144:147], v[32:35]
	v_exp_f32_e32 v112, v112
	v_exp_f32_e32 v113, v113
	v_mfma_f32_16x16x32_bf16 v[36:39], v[214:217], v[148:151], v[36:39]
	v_exp_f32_e32 v114, v114
	v_exp_f32_e32 v115, v115
	v_exp_f32_e32 v108, v108
	v_mfma_f32_16x16x32_bf16 v[40:43], v[218:221], v[144:147], v[40:43]
	v_exp_f32_e32 v109, v109
	v_exp_f32_e32 v110, v110
	v_mfma_f32_16x16x32_bf16 v[60:63], v[218:221], v[148:151], v[60:63]
	v_exp_f32_e32 v111, v111
	v_exp_f32_e32 v116, v116
	v_exp_f32_e32 v117, v117
	v_mfma_f32_16x16x32_bf16 v[44:47], v[222:225], v[144:147], v[44:47]
	v_exp_f32_e32 v118, v118
	v_exp_f32_e32 v119, v119
	v_mfma_f32_16x16x32_bf16 v[64:67], v[222:225], v[148:151], v[64:67]
	v_cvt_pk_bf16_f32 v136, v104, v105
	v_cvt_pk_bf16_f32 v137, v106, v107
	v_cvt_pk_bf16_f32 v138, v112, v113
	v_mfma_f32_16x16x32_bf16 v[48:51], v[226:229], v[144:147], v[48:51]
	v_cvt_pk_bf16_f32 v139, v114, v115
	v_cvt_pk_bf16_f32 v140, v108, v109
	v_mfma_f32_16x16x32_bf16 v[52:55], v[226:229], v[148:151], v[52:55]
	v_cvt_pk_bf16_f32 v141, v110, v111
	v_cvt_pk_bf16_f32 v142, v116, v117
	v_cvt_pk_bf16_f32 v143, v118, v119
	ds_read_b64 v[214:215], v180 offset:28864
	ds_read_b64 v[216:217], v180 offset:28896
	ds_read_b64 v[218:219], v180 offset:33216
	ds_read_b64 v[220:221], v180 offset:33248
	ds_read_b64 v[222:223], v180 offset:37568
	ds_read_b64 v[224:225], v180 offset:37600
	ds_read_b64 v[226:227], v180 offset:41920
	ds_read_b64 v[228:229], v180 offset:41952
	s_nop 1
	v_mfma_f32_16x16x32_bf16 v[68:71], v[152:155], v[136:139], v[68:71]
	v_exp_f32_e32 v120, v120
	v_exp_f32_e32 v121, v121
	v_mfma_f32_16x16x32_bf16 v[56:59], v[152:155], v[140:143], v[56:59]
	v_exp_f32_e32 v122, v122
	v_exp_f32_e32 v123, v123
	s_waitcnt lgkmcnt(8)
	v_mfma_f32_16x16x32_bf16 v[32:35], v[198:201], v[136:139], v[32:35]
	v_exp_f32_e32 v128, v128
	v_exp_f32_e32 v129, v129
	v_mfma_f32_16x16x32_bf16 v[36:39], v[198:201], v[140:143], v[36:39]
	v_exp_f32_e32 v130, v130
	v_exp_f32_e32 v131, v131
	v_exp_f32_e32 v124, v124
	v_mfma_f32_16x16x32_bf16 v[40:43], v[202:205], v[136:139], v[40:43]
	v_exp_f32_e32 v125, v125
	v_exp_f32_e32 v126, v126
	v_mfma_f32_16x16x32_bf16 v[60:63], v[202:205], v[140:143], v[60:63]
	v_exp_f32_e32 v127, v127
	v_exp_f32_e32 v132, v132
	v_exp_f32_e32 v133, v133
	v_mfma_f32_16x16x32_bf16 v[44:47], v[206:209], v[136:139], v[44:47]
	v_exp_f32_e32 v134, v134
	v_exp_f32_e32 v135, v135
	v_mfma_f32_16x16x32_bf16 v[64:67], v[206:209], v[140:143], v[64:67]
	v_cvt_pk_bf16_f32 v144, v120, v121
	v_cvt_pk_bf16_f32 v145, v122, v123
	v_cvt_pk_bf16_f32 v146, v128, v129
	v_mfma_f32_16x16x32_bf16 v[48:51], v[210:213], v[136:139], v[48:51]
	v_cvt_pk_bf16_f32 v147, v130, v131
	v_cvt_pk_bf16_f32 v148, v124, v125
	v_mfma_f32_16x16x32_bf16 v[52:55], v[210:213], v[140:143], v[52:55]
	v_cvt_pk_bf16_f32 v149, v126, v127
	v_cvt_pk_bf16_f32 v150, v132, v133
	v_cvt_pk_bf16_f32 v151, v134, v135
	s_nop 1
	v_mfma_f32_16x16x32_bf16 v[68:71], v[152:155], v[144:147], v[68:71]
	v_mfma_f32_16x16x32_bf16 v[56:59], v[152:155], v[148:151], v[56:59]
	s_waitcnt lgkmcnt(0)
	v_mfma_f32_16x16x32_bf16 v[32:35], v[214:217], v[144:147], v[32:35]
	v_mfma_f32_16x16x32_bf16 v[36:39], v[214:217], v[148:151], v[36:39]
	v_mfma_f32_16x16x32_bf16 v[40:43], v[218:221], v[144:147], v[40:43]
	v_mfma_f32_16x16x32_bf16 v[60:63], v[218:221], v[148:151], v[60:63]
	v_mfma_f32_16x16x32_bf16 v[44:47], v[222:225], v[144:147], v[44:47]
	v_mfma_f32_16x16x32_bf16 v[64:67], v[222:225], v[148:151], v[64:67]
	v_mfma_f32_16x16x32_bf16 v[48:51], v[226:229], v[144:147], v[48:51]
	v_mfma_f32_16x16x32_bf16 v[52:55], v[226:229], v[148:151], v[52:55]
	s_waitcnt lgkmcnt(0)
	s_barrier
	s_mov_b32 s18, s15
	s_mov_b32 s15, s12
	s_mov_b32 s12, s9
	s_mov_b32 s9, s18
	s_add_i32 s13, s13, 1
	s_cmp_lg_u32 s13, 16
	s_cbranch_scc1 .Lattn_a_loop
	global_load_dwordx4 v[230:233], v[164:165], off
	global_load_dwordx4 v[234:237], v[166:167], off
	global_load_dwordx4 v[238:241], v[168:169], off
	global_load_dwordx4 v[242:245], v[170:171], off
	global_load_dwordx4 v[246:249], v[172:173], off
	v_lshl_add_u64 v[164:165], v[164:165], 0, s[26:27]
	v_lshl_add_u64 v[166:167], v[166:167], 0, s[26:27]
	v_lshl_add_u64 v[168:169], v[168:169], 0, s[16:17]
	v_lshl_add_u64 v[170:171], v[170:171], 0, s[16:17]
	v_lshl_add_u64 v[172:173], v[172:173], 0, s[16:17]
	v_add_u32_e32 v184, s9, v159
	v_add_u32_e32 v185, s9, v161
	v_add_u32_e32 v186, s9, v163
	v_add_u32_e32 v187, s9, v160
	v_add_u32_e32 v188, s9, v162
	v_add3_u32 v179, s12, v156, v181
	ds_read_b128 v[198:201], v179
	ds_read_b128 v[202:205], v179 offset:3584
	ds_read_b128 v[206:209], v179 offset:7168
	ds_read_b128 v[210:213], v179 offset:10752
	ds_read_b128 v[214:217], v179 offset:64
	ds_read_b128 v[218:221], v179 offset:3648
	ds_read_b128 v[222:225], v179 offset:7232
	ds_read_b128 v[226:229], v179 offset:10816
	s_waitcnt lgkmcnt(7)
	v_mfma_f32_16x16x32_bf16 v[72:75], v[198:201], v[12:15], v[24:27]
	v_mfma_f32_16x16x32_bf16 v[76:79], v[198:201], v[20:23], v[28:31]
	ds_read_b128 v[198:201], v179 offset:128
	s_waitcnt lgkmcnt(7)
	v_mfma_f32_16x16x32_bf16 v[80:83], v[202:205], v[12:15], v[24:27]
	v_mfma_f32_16x16x32_bf16 v[84:87], v[202:205], v[20:23], v[28:31]
	ds_read_b128 v[202:205], v179 offset:3712
	s_waitcnt lgkmcnt(7)
	v_mfma_f32_16x16x32_bf16 v[88:91], v[206:209], v[12:15], v[24:27]
	v_mfma_f32_16x16x32_bf16 v[92:95], v[206:209], v[20:23], v[28:31]
	ds_read_b128 v[206:209], v179 offset:7296
	s_waitcnt lgkmcnt(7)
	v_mfma_f32_16x16x32_bf16 v[96:99], v[210:213], v[12:15], v[24:27]
	v_mfma_f32_16x16x32_bf16 v[100:103], v[210:213], v[20:23], v[28:31]
	ds_read_b128 v[210:213], v179 offset:10880
	s_waitcnt lgkmcnt(7)
; DEV float ex2(float x) { return __builtin_amdgcn_exp2f(x); }
; DEV void attn_item(const Params& p, int bl, int head, int q0, int nkeys, char* smem, int tid) {
;     ...
;     for (int hh = 0; hh < 2; ++hh) {
;       f32x4 s[4][2];
; #pragma unroll
;       for (int kf = 0; kf < 4; ++kf) {
; #pragma unroll
;         for (int ks = 0; ks < 3; ++ks) {
;           bf16x8 a = *(const bf16x8*)(kb + (hh * 64 + kf * 16 + fr) * KROW + ks * 64 + fq * 16);
;           s[kf][0] = __builtin_amdgcn_mfma_f32_16x16x32_bf16(a, qf[0][ks], ks == 0 ? negm[0] : s[kf][0], 0, 0, 0);
;           s[kf][1] = __builtin_amdgcn_mfma_f32_16x16x32_bf16(a, qf[1][ks], ks == 0 ? negm[1] : s[kf][1], 0, 0, 0);
;         }
;       }
; #pragma unroll
;       for (int kk = 0; kk < 2; ++kk) {
;         bf16x8 pb[2];
; #pragma unroll
;         for (int qt = 0; qt < 2; ++qt) {
;           const float e0 = ex2(s[2 * kk][qt][0]), e1 = ex2(s[2 * kk][qt][1]), e2 = ex2(s[2 * kk][qt][2]), e3 = ex2(s[2 * kk][qt][3]);
;           const float e4 = ex2(s[2 * kk + 1][qt][0]), e5 = ex2(s[2 * kk + 1][qt][1]), e6 = ex2(s[2 * kk + 1][qt][2]), e7 = ex2(s[2 * kk + 1][qt][3]);
;           u32x4 cw = {pack2(e0, e1), pack2(e2, e3), pack2(e4, e5), pack2(e6, e7)};
;           pb[qt] = __builtin_bit_cast(bf16x8, cw);
;         }
;         lacc[0] = __builtin_amdgcn_mfma_f32_16x16x32_bf16(ones, pb[0], lacc[0], 0, 0, 0);
;         lacc[1] = __builtin_amdgcn_mfma_f32_16x16x32_bf16(ones, pb[1], lacc[1], 0, 0, 0);
; #pragma unroll
;         for (int dvf = 0; dvf < 4; ++dvf) {
;           const char* vp = vb + (dvf * 16 + fr) * VROW + (hh * 64 + kk * 32 + fq * 4) * 2;
;           const uint2 h0 = *(const uint2*)vp, h1 = *(const uint2*)(vp + 32);
;           u32x4 vw = {h0.x, h0.y, h1.x, h1.y};
;           const bf16x8 va = __builtin_bit_cast(bf16x8, vw);
;           o[dvf][0] = __builtin_amdgcn_mfma_f32_16x16x32_bf16(va, pb[0], o[dvf][0], 0, 0, 0);
;           o[dvf][1] = __builtin_amdgcn_mfma_f32_16x16x32_bf16(va, pb[1], o[dvf][1], 0, 0, 0);
;         }
;       }
;     }
;     if (t + 1 < nt) {
;       char* nb = smem + ((t + 1) & 1) * ASTG;
; #pragma unroll
;       for (int i = 0; i < 3; ++i) *(u32x4*)(nb + koff[i]) = kr[i];
; #pragma unroll
;       for (int i = 0; i < 2; ++i) *(u32x4*)(nb + KBYTES + voffl[i]) = vr[i];
;     }
	v_mfma_f32_16x16x32_bf16 v[72:75], v[214:217], v[8:11], v[72:75]
	v_mfma_f32_16x16x32_bf16 v[76:79], v[214:217], v[16:19], v[76:79]
	ds_read_b128 v[214:217], v179 offset:14336
	s_waitcnt lgkmcnt(7)
	v_mfma_f32_16x16x32_bf16 v[80:83], v[218:221], v[8:11], v[80:83]
	v_mfma_f32_16x16x32_bf16 v[84:87], v[218:221], v[16:19], v[84:87]
	ds_read_b128 v[218:221], v179 offset:17920
	s_waitcnt lgkmcnt(7)
	v_mfma_f32_16x16x32_bf16 v[88:91], v[222:225], v[8:11], v[88:91]
	v_mfma_f32_16x16x32_bf16 v[92:95], v[222:225], v[16:19], v[92:95]
	ds_read_b128 v[222:225], v179 offset:21504
	s_waitcnt lgkmcnt(7)
	v_mfma_f32_16x16x32_bf16 v[96:99], v[226:229], v[8:11], v[96:99]
	v_mfma_f32_16x16x32_bf16 v[100:103], v[226:229], v[16:19], v[100:103]
	ds_read_b128 v[226:229], v179 offset:25088
	s_waitcnt lgkmcnt(7)
	v_mfma_f32_16x16x32_bf16 v[72:75], v[198:201], v[4:7], v[72:75]
	v_mfma_f32_16x16x32_bf16 v[76:79], v[198:201], v[0:3], v[76:79]
	ds_read_b128 v[198:201], v179 offset:14400
	s_waitcnt lgkmcnt(7)
	v_mfma_f32_16x16x32_bf16 v[80:83], v[202:205], v[4:7], v[80:83]
	v_mfma_f32_16x16x32_bf16 v[84:87], v[202:205], v[0:3], v[84:87]
	ds_read_b128 v[202:205], v179 offset:17984
	s_waitcnt lgkmcnt(7)
	v_mfma_f32_16x16x32_bf16 v[88:91], v[206:209], v[4:7], v[88:91]
	v_mfma_f32_16x16x32_bf16 v[92:95], v[206:209], v[0:3], v[92:95]
	ds_read_b128 v[206:209], v179 offset:21568
	s_waitcnt lgkmcnt(7)
	v_mfma_f32_16x16x32_bf16 v[96:99], v[210:213], v[4:7], v[96:99]
	v_mfma_f32_16x16x32_bf16 v[100:103], v[210:213], v[0:3], v[100:103]
	ds_read_b128 v[210:213], v179 offset:25152
	s_waitcnt lgkmcnt(7)
	v_mfma_f32_16x16x32_bf16 v[104:107], v[214:217], v[12:15], v[24:27]
	v_mfma_f32_16x16x32_bf16 v[108:111], v[214:217], v[20:23], v[28:31]
	ds_read_b128 v[214:217], v179 offset:14464
	s_waitcnt lgkmcnt(7)
	v_mfma_f32_16x16x32_bf16 v[112:115], v[218:221], v[12:15], v[24:27]
	v_mfma_f32_16x16x32_bf16 v[116:119], v[218:221], v[20:23], v[28:31]
	ds_read_b128 v[218:221], v179 offset:18048
	s_waitcnt lgkmcnt(7)
	v_mfma_f32_16x16x32_bf16 v[120:123], v[222:225], v[12:15], v[24:27]
	v_exp_f32_e32 v72, v72
	v_mfma_f32_16x16x32_bf16 v[124:127], v[222:225], v[20:23], v[28:31]
	v_exp_f32_e32 v73, v73
	ds_read_b128 v[222:225], v179 offset:21632
	s_waitcnt lgkmcnt(7)
	v_mfma_f32_16x16x32_bf16 v[128:131], v[226:229], v[12:15], v[24:27]
	v_exp_f32_e32 v74, v74
	v_mfma_f32_16x16x32_bf16 v[132:135], v[226:229], v[20:23], v[28:31]
	v_exp_f32_e32 v75, v75
	ds_read_b128 v[226:229], v179 offset:25216
	s_waitcnt lgkmcnt(7)
	v_mfma_f32_16x16x32_bf16 v[104:107], v[198:201], v[8:11], v[104:107]
	v_exp_f32_e32 v80, v80
	v_exp_f32_e32 v81, v81
	v_mfma_f32_16x16x32_bf16 v[108:111], v[198:201], v[16:19], v[108:111]
	v_exp_f32_e32 v82, v82
	s_waitcnt lgkmcnt(6)
	v_mfma_f32_16x16x32_bf16 v[112:115], v[202:205], v[8:11], v[112:115]
	v_exp_f32_e32 v83, v83
	v_mfma_f32_16x16x32_bf16 v[116:119], v[202:205], v[16:19], v[116:119]
	v_exp_f32_e32 v76, v76
	s_waitcnt lgkmcnt(5)
	v_mfma_f32_16x16x32_bf16 v[120:123], v[206:209], v[8:11], v[120:123]
	v_exp_f32_e32 v77, v77
	v_mfma_f32_16x16x32_bf16 v[124:127], v[206:209], v[16:19], v[124:127]
	v_exp_f32_e32 v78, v78
	v_exp_f32_e32 v79, v79
	s_waitcnt lgkmcnt(4)
	v_mfma_f32_16x16x32_bf16 v[128:131], v[210:213], v[8:11], v[128:131]
	v_exp_f32_e32 v84, v84
	v_mfma_f32_16x16x32_bf16 v[132:135], v[210:213], v[16:19], v[132:135]
	v_exp_f32_e32 v85, v85
	s_waitcnt lgkmcnt(3)
	v_mfma_f32_16x16x32_bf16 v[104:107], v[214:217], v[4:7], v[104:107]
	v_exp_f32_e32 v86, v86
	v_mfma_f32_16x16x32_bf16 v[108:111], v[214:217], v[0:3], v[108:111]
	v_exp_f32_e32 v87, v87
	s_waitcnt lgkmcnt(2)
	v_mfma_f32_16x16x32_bf16 v[112:115], v[218:221], v[4:7], v[112:115]
	v_cvt_pk_bf16_f32 v136, v72, v73
	v_cvt_pk_bf16_f32 v137, v74, v75
	v_mfma_f32_16x16x32_bf16 v[116:119], v[218:221], v[0:3], v[116:119]
	v_cvt_pk_bf16_f32 v138, v80, v81
	s_waitcnt lgkmcnt(1)
	v_mfma_f32_16x16x32_bf16 v[120:123], v[222:225], v[4:7], v[120:123]
	v_cvt_pk_bf16_f32 v139, v82, v83
	v_mfma_f32_16x16x32_bf16 v[124:127], v[222:225], v[0:3], v[124:127]
	v_cvt_pk_bf16_f32 v140, v76, v77
	s_waitcnt lgkmcnt(0)
	v_mfma_f32_16x16x32_bf16 v[128:131], v[226:229], v[4:7], v[128:131]
	v_cvt_pk_bf16_f32 v141, v78, v79
	v_mfma_f32_16x16x32_bf16 v[132:135], v[226:229], v[0:3], v[132:135]
	v_cvt_pk_bf16_f32 v142, v84, v85
	v_cvt_pk_bf16_f32 v143, v86, v87
	s_waitcnt vmcnt(0)
	ds_write_b128 v184, v[238:241]
	ds_write_b128 v185, v[242:245]
	ds_write_b128 v186, v[246:249]
	ds_write_b128 v187, v[230:233] offset:26624
	ds_write_b128 v188, v[234:237] offset:26624
	v_add3_u32 v180, s12, v176, v177
	ds_read_b64 v[198:199], v180 offset:28672
	ds_read_b64 v[200:201], v180 offset:28704
	ds_read_b64 v[202:203], v180 offset:33024
	ds_read_b64 v[204:205], v180 offset:33056
	ds_read_b64 v[206:207], v180 offset:37376
	ds_read_b64 v[208:209], v180 offset:37408
	ds_read_b64 v[210:211], v180 offset:41728
	ds_read_b64 v[212:213], v180 offset:41760
	ds_read_b64 v[214:215], v180 offset:28736
	ds_read_b64 v[216:217], v180 offset:28768
	ds_read_b64 v[218:219], v180 offset:33088
	ds_read_b64 v[220:221], v180 offset:33120
	ds_read_b64 v[222:223], v180 offset:37440
	ds_read_b64 v[224:225], v180 offset:37472
	ds_read_b64 v[226:227], v180 offset:41792
	ds_read_b64 v[228:229], v180 offset:41824
	v_mfma_f32_16x16x32_bf16 v[68:71], v[152:155], v[136:139], v[68:71]
	v_exp_f32_e32 v88, v88
	v_exp_f32_e32 v89, v89
	v_mfma_f32_16x16x32_bf16 v[56:59], v[152:155], v[140:143], v[56:59]
	v_exp_f32_e32 v90, v90
	v_exp_f32_e32 v91, v91
	s_waitcnt lgkmcnt(8)
; DEV float ex2(float x) { return __builtin_amdgcn_exp2f(x); }
; DEV void attn_item(const Params& p, int bl, int head, int q0, int nkeys, char* smem, int tid) {
;     ...
; #pragma unroll
;       for (int kk = 0; kk < 2; ++kk) {
;         bf16x8 pb[2];
; #pragma unroll
;         for (int qt = 0; qt < 2; ++qt) {
;           const float e0 = ex2(s[2 * kk][qt][0]), e1 = ex2(s[2 * kk][qt][1]), e2 = ex2(s[2 * kk][qt][2]), e3 = ex2(s[2 * kk][qt][3]);
;           const float e4 = ex2(s[2 * kk + 1][qt][0]), e5 = ex2(s[2 * kk + 1][qt][1]), e6 = ex2(s[2 * kk + 1][qt][2]), e7 = ex2(s[2 * kk + 1][qt][3]);
;           u32x4 cw = {pack2(e0, e1), pack2(e2, e3), pack2(e4, e5), pack2(e6, e7)};
;           pb[qt] = __builtin_bit_cast(bf16x8, cw);
;         }
;         lacc[0] = __builtin_amdgcn_mfma_f32_16x16x32_bf16(ones, pb[0], lacc[0], 0, 0, 0);
;         lacc[1] = __builtin_amdgcn_mfma_f32_16x16x32_bf16(ones, pb[1], lacc[1], 0, 0, 0);
; #pragma unroll
;         for (int dvf = 0; dvf < 4; ++dvf) {
;           const char* vp = vb + (dvf * 16 + fr) * VROW + (hh * 64 + kk * 32 + fq * 4) * 2;
;           const uint2 h0 = *(const uint2*)vp, h1 = *(const uint2*)(vp + 32);
;           u32x4 vw = {h0.x, h0.y, h1.x, h1.y};
;           const bf16x8 va = __builtin_bit_cast(bf16x8, vw);
;           o[dvf][0] = __builtin_amdgcn_mfma_f32_16x16x32_bf16(va, pb[0], o[dvf][0], 0, 0, 0);
;           o[dvf][1] = __builtin_amdgcn_mfma_f32_16x16x32_bf16(va, pb[1], o[dvf][1], 0, 0, 0);
;         }
;       }
;     }
;     if (t + 1 < nt) {
;       char* nb = smem + ((t + 1) & 1) * ASTG;
; #pragma unroll
;       for (int i = 0; i < 3; ++i) *(u32x4*)(nb + koff[i]) = kr[i];
; #pragma unroll
;       for (int i = 0; i < 2; ++i) *(u32x4*)(nb + KBYTES + voffl[i]) = vr[i];
;     }
;     __syncthreads();
	v_mfma_f32_16x16x32_bf16 v[32:35], v[198:201], v[136:139], v[32:35]
	v_exp_f32_e32 v96, v96
	v_exp_f32_e32 v97, v97
	v_mfma_f32_16x16x32_bf16 v[36:39], v[198:201], v[140:143], v[36:39]
	v_exp_f32_e32 v98, v98
	v_exp_f32_e32 v99, v99
	v_exp_f32_e32 v92, v92
	v_mfma_f32_16x16x32_bf16 v[40:43], v[202:205], v[136:139], v[40:43]
	v_exp_f32_e32 v93, v93
	v_exp_f32_e32 v94, v94
	v_mfma_f32_16x16x32_bf16 v[60:63], v[202:205], v[140:143], v[60:63]
	v_exp_f32_e32 v95, v95
	v_exp_f32_e32 v100, v100
	v_exp_f32_e32 v101, v101
	v_mfma_f32_16x16x32_bf16 v[44:47], v[206:209], v[136:139], v[44:47]
	v_exp_f32_e32 v102, v102
	v_exp_f32_e32 v103, v103
	v_mfma_f32_16x16x32_bf16 v[64:67], v[206:209], v[140:143], v[64:67]
	v_cvt_pk_bf16_f32 v144, v88, v89
	v_cvt_pk_bf16_f32 v145, v90, v91
	v_cvt_pk_bf16_f32 v146, v96, v97
	v_mfma_f32_16x16x32_bf16 v[48:51], v[210:213], v[136:139], v[48:51]
	v_cvt_pk_bf16_f32 v147, v98, v99
	v_cvt_pk_bf16_f32 v148, v92, v93
	v_mfma_f32_16x16x32_bf16 v[52:55], v[210:213], v[140:143], v[52:55]
	v_cvt_pk_bf16_f32 v149, v94, v95
	v_cvt_pk_bf16_f32 v150, v100, v101
	v_cvt_pk_bf16_f32 v151, v102, v103
	ds_read_b64 v[198:199], v180 offset:28800
	ds_read_b64 v[200:201], v180 offset:28832
	ds_read_b64 v[202:203], v180 offset:33152
	ds_read_b64 v[204:205], v180 offset:33184
	ds_read_b64 v[206:207], v180 offset:37504
	ds_read_b64 v[208:209], v180 offset:37536
	ds_read_b64 v[210:211], v180 offset:41856
	ds_read_b64 v[212:213], v180 offset:41888
	s_nop 1
	v_mfma_f32_16x16x32_bf16 v[68:71], v[152:155], v[144:147], v[68:71]
	v_exp_f32_e32 v104, v104
	v_exp_f32_e32 v105, v105
	v_mfma_f32_16x16x32_bf16 v[56:59], v[152:155], v[148:151], v[56:59]
	v_exp_f32_e32 v106, v106
	v_exp_f32_e32 v107, v107
	s_waitcnt lgkmcnt(8)
	v_mfma_f32_16x16x32_bf16 v[32:35], v[214:217], v[144:147], v[32:35]
	v_exp_f32_e32 v112, v112
	v_exp_f32_e32 v113, v113
	v_mfma_f32_16x16x32_bf16 v[36:39], v[214:217], v[148:151], v[36:39]
	v_exp_f32_e32 v114, v114
	v_exp_f32_e32 v115, v115
	v_exp_f32_e32 v108, v108
	v_mfma_f32_16x16x32_bf16 v[40:43], v[218:221], v[144:147], v[40:43]
	v_exp_f32_e32 v109, v109
	v_exp_f32_e32 v110, v110
	v_mfma_f32_16x16x32_bf16 v[60:63], v[218:221], v[148:151], v[60:63]
	v_exp_f32_e32 v111, v111
	v_exp_f32_e32 v116, v116
	v_exp_f32_e32 v117, v117
	v_mfma_f32_16x16x32_bf16 v[44:47], v[222:225], v[144:147], v[44:47]
	v_exp_f32_e32 v118, v118
	v_exp_f32_e32 v119, v119
	v_mfma_f32_16x16x32_bf16 v[64:67], v[222:225], v[148:151], v[64:67]
	v_cvt_pk_bf16_f32 v136, v104, v105
	v_cvt_pk_bf16_f32 v137, v106, v107
	v_cvt_pk_bf16_f32 v138, v112, v113
	v_mfma_f32_16x16x32_bf16 v[48:51], v[226:229], v[144:147], v[48:51]
	v_cvt_pk_bf16_f32 v139, v114, v115
	v_cvt_pk_bf16_f32 v140, v108, v109
	v_mfma_f32_16x16x32_bf16 v[52:55], v[226:229], v[148:151], v[52:55]
	v_cvt_pk_bf16_f32 v141, v110, v111
	v_cvt_pk_bf16_f32 v142, v116, v117
	v_cvt_pk_bf16_f32 v143, v118, v119
	ds_read_b64 v[214:215], v180 offset:28864
	ds_read_b64 v[216:217], v180 offset:28896
	ds_read_b64 v[218:219], v180 offset:33216
	ds_read_b64 v[220:221], v180 offset:33248
	ds_read_b64 v[222:223], v180 offset:37568
	ds_read_b64 v[224:225], v180 offset:37600
	ds_read_b64 v[226:227], v180 offset:41920
	ds_read_b64 v[228:229], v180 offset:41952
	s_nop 1
	v_mfma_f32_16x16x32_bf16 v[68:71], v[152:155], v[136:139], v[68:71]
	v_exp_f32_e32 v120, v120
	v_exp_f32_e32 v121, v121
	v_mfma_f32_16x16x32_bf16 v[56:59], v[152:155], v[140:143], v[56:59]
	v_exp_f32_e32 v122, v122
	v_exp_f32_e32 v123, v123
	s_waitcnt lgkmcnt(8)
	v_mfma_f32_16x16x32_bf16 v[32:35], v[198:201], v[136:139], v[32:35]
	v_exp_f32_e32 v128, v128
	v_exp_f32_e32 v129, v129
	v_mfma_f32_16x16x32_bf16 v[36:39], v[198:201], v[140:143], v[36:39]
	v_exp_f32_e32 v130, v130
	v_exp_f32_e32 v131, v131
	v_exp_f32_e32 v124, v124
	v_mfma_f32_16x16x32_bf16 v[40:43], v[202:205], v[136:139], v[40:43]
	v_exp_f32_e32 v125, v125
	v_exp_f32_e32 v126, v126
	v_mfma_f32_16x16x32_bf16 v[60:63], v[202:205], v[140:143], v[60:63]
	v_exp_f32_e32 v127, v127
	v_exp_f32_e32 v132, v132
	v_exp_f32_e32 v133, v133
	v_mfma_f32_16x16x32_bf16 v[44:47], v[206:209], v[136:139], v[44:47]
	v_exp_f32_e32 v134, v134
	v_exp_f32_e32 v135, v135
	v_mfma_f32_16x16x32_bf16 v[64:67], v[206:209], v[140:143], v[64:67]
	v_cvt_pk_bf16_f32 v144, v120, v121
	v_cvt_pk_bf16_f32 v145, v122, v123
	v_cvt_pk_bf16_f32 v146, v128, v129
	v_mfma_f32_16x16x32_bf16 v[48:51], v[210:213], v[136:139], v[48:51]
	v_cvt_pk_bf16_f32 v147, v130, v131
	v_cvt_pk_bf16_f32 v148, v124, v125
	v_mfma_f32_16x16x32_bf16 v[52:55], v[210:213], v[140:143], v[52:55]
	v_cvt_pk_bf16_f32 v149, v126, v127
	v_cvt_pk_bf16_f32 v150, v132, v133
	v_cvt_pk_bf16_f32 v151, v134, v135
	s_nop 1
	v_mfma_f32_16x16x32_bf16 v[68:71], v[152:155], v[144:147], v[68:71]
	v_mfma_f32_16x16x32_bf16 v[56:59], v[152:155], v[148:151], v[56:59]
	s_waitcnt lgkmcnt(0)
	v_mfma_f32_16x16x32_bf16 v[32:35], v[214:217], v[144:147], v[32:35]
	v_mfma_f32_16x16x32_bf16 v[36:39], v[214:217], v[148:151], v[36:39]
	v_mfma_f32_16x16x32_bf16 v[40:43], v[218:221], v[144:147], v[40:43]
	v_mfma_f32_16x16x32_bf16 v[60:63], v[218:221], v[148:151], v[60:63]
	v_mfma_f32_16x16x32_bf16 v[44:47], v[222:225], v[144:147], v[44:47]
	v_mfma_f32_16x16x32_bf16 v[64:67], v[222:225], v[148:151], v[64:67]
	v_mfma_f32_16x16x32_bf16 v[48:51], v[226:229], v[144:147], v[48:51]
	v_mfma_f32_16x16x32_bf16 v[52:55], v[226:229], v[148:151], v[52:55]
	s_waitcnt lgkmcnt(0)
	s_barrier
	s_mov_b32 s18, s15
	s_mov_b32 s15, s12
	s_mov_b32 s12, s9
	s_mov_b32 s9, s18
	s_add_i32 s13, s13, 1
; DEV float ex2(float x) { return __builtin_amdgcn_exp2f(x); }
; DEV void attn_item(const Params& p, int bl, int head, int q0, int nkeys, char* smem, int tid) {
;     ...
;     for (int hh = 0; hh < 2; ++hh) {
;       f32x4 s[4][2];
; #pragma unroll
;       for (int kf = 0; kf < 4; ++kf) {
; #pragma unroll
;         for (int ks = 0; ks < 3; ++ks) {
;           bf16x8 a = *(const bf16x8*)(kb + (hh * 64 + kf * 16 + fr) * KROW + ks * 64 + fq * 16);
;           s[kf][0] = __builtin_amdgcn_mfma_f32_16x16x32_bf16(a, qf[0][ks], ks == 0 ? negm[0] : s[kf][0], 0, 0, 0);
;           s[kf][1] = __builtin_amdgcn_mfma_f32_16x16x32_bf16(a, qf[1][ks], ks == 0 ? negm[1] : s[kf][1], 0, 0, 0);
;         }
;       }
; #pragma unroll
;       for (int kk = 0; kk < 2; ++kk) {
;         bf16x8 pb[2];
; #pragma unroll
;         for (int qt = 0; qt < 2; ++qt) {
;           const float e0 = ex2(s[2 * kk][qt][0]), e1 = ex2(s[2 * kk][qt][1]), e2 = ex2(s[2 * kk][qt][2]), e3 = ex2(s[2 * kk][qt][3]);
;           const float e4 = ex2(s[2 * kk + 1][qt][0]), e5 = ex2(s[2 * kk + 1][qt][1]), e6 = ex2(s[2 * kk + 1][qt][2]), e7 = ex2(s[2 * kk + 1][qt][3]);
;           u32x4 cw = {pack2(e0, e1), pack2(e2, e3), pack2(e4, e5), pack2(e6, e7)};
;           pb[qt] = __builtin_bit_cast(bf16x8, cw);
;         }
;         lacc[0] = __builtin_amdgcn_mfma_f32_16x16x32_bf16(ones, pb[0], lacc[0], 0, 0, 0);
;         lacc[1] = __builtin_amdgcn_mfma_f32_16x16x32_bf16(ones, pb[1], lacc[1], 0, 0, 0);
; #pragma unroll
;         for (int dvf = 0; dvf < 4; ++dvf) {
;           const char* vp = vb + (dvf * 16 + fr) * VROW + (hh * 64 + kk * 32 + fq * 4) * 2;
;           const uint2 h0 = *(const uint2*)vp, h1 = *(const uint2*)(vp + 32);
;           u32x4 vw = {h0.x, h0.y, h1.x, h1.y};
;           const bf16x8 va = __builtin_bit_cast(bf16x8, vw);
;           o[dvf][0] = __builtin_amdgcn_mfma_f32_16x16x32_bf16(va, pb[0], o[dvf][0], 0, 0, 0);
;           o[dvf][1] = __builtin_amdgcn_mfma_f32_16x16x32_bf16(va, pb[1], o[dvf][1], 0, 0, 0);
;         }
.Lattn_tail:
	s_mov_b32 s9, s12
	s_nop 7
	v_add3_u32 v108, s9, v156, v178
	ds_read_b128 v[72:75], v108
	ds_read_b128 v[80:83], v108 offset:64
	s_ashr_i32 s6, s11, 3
	s_ashr_i32 s7, s6, 31
	s_waitcnt lgkmcnt(1)
	v_mfma_f32_16x16x32_bf16 v[76:79], v[72:75], v[12:15], v[24:27]
	ds_read_b128 v[88:91], v108 offset:3392
	ds_read_b128 v[96:99], v108 offset:6720
	ds_read_b128 v[104:107], v108 offset:10048
	v_mfma_f32_16x16x32_bf16 v[72:75], v[72:75], v[20:23], v[28:31]
	s_waitcnt lgkmcnt(3)
	v_mfma_f32_16x16x32_bf16 v[76:79], v[80:83], v[8:11], v[76:79]
	v_mfma_f32_16x16x32_bf16 v[72:75], v[80:83], v[16:19], v[72:75]
	ds_read_b128 v[80:83], v108 offset:128
	s_waitcnt lgkmcnt(0)
	v_mfma_f32_16x16x32_bf16 v[76:79], v[80:83], v[4:7], v[76:79]
	s_nop 7
	v_exp_f32_e32 v76, v76
	v_mfma_f32_16x16x32_bf16 v[72:75], v[80:83], v[0:3], v[72:75]
	ds_read_b128 v[80:83], v108 offset:3328
	v_exp_f32_e32 v77, v77
	v_exp_f32_e32 v78, v78
	s_waitcnt lgkmcnt(0)
	v_mfma_f32_16x16x32_bf16 v[84:87], v[80:83], v[12:15], v[24:27]
	v_exp_f32_e32 v79, v79
	v_cvt_pk_bf16_f32 v76, v76, v77
	s_nop 0
	v_exp_f32_e32 v72, v72
	v_mfma_f32_16x16x32_bf16 v[80:83], v[80:83], v[20:23], v[28:31]
	v_cvt_pk_bf16_f32 v77, v78, v79
	v_exp_f32_e32 v73, v73
	v_exp_f32_e32 v74, v74
	v_mfma_f32_16x16x32_bf16 v[84:87], v[88:91], v[8:11], v[84:87]
	v_exp_f32_e32 v75, v75
	v_cvt_pk_bf16_f32 v72, v72, v73
	v_cvt_pk_bf16_f32 v73, v74, v75
	v_mfma_f32_16x16x32_bf16 v[80:83], v[88:91], v[16:19], v[80:83]
	ds_read_b128 v[88:91], v108 offset:3456
	s_waitcnt lgkmcnt(0)
	v_mfma_f32_16x16x32_bf16 v[84:87], v[88:91], v[4:7], v[84:87]
	s_nop 7
	v_exp_f32_e32 v84, v84
	v_mfma_f32_16x16x32_bf16 v[80:83], v[88:91], v[0:3], v[80:83]
	ds_read_b128 v[88:91], v108 offset:6656
	v_exp_f32_e32 v85, v85
	v_exp_f32_e32 v86, v86
	s_waitcnt lgkmcnt(0)
	v_mfma_f32_16x16x32_bf16 v[92:95], v[88:91], v[12:15], v[24:27]
	v_exp_f32_e32 v87, v87
	v_cvt_pk_bf16_f32 v78, v84, v85
	s_nop 0
	v_exp_f32_e32 v109, v82
	v_mfma_f32_16x16x32_bf16 v[88:91], v[88:91], v[20:23], v[28:31]
	v_cvt_pk_bf16_f32 v79, v86, v87
	v_exp_f32_e32 v110, v83
	v_mfma_f32_16x16x32_bf16 v[92:95], v[96:99], v[8:11], v[92:95]
	v_cvt_pk_bf16_f32 v75, v109, v110
	v_mfma_f32_16x16x32_bf16 v[88:91], v[96:99], v[16:19], v[88:91]
	ds_read_b128 v[96:99], v108 offset:6784
	s_waitcnt lgkmcnt(0)
	v_mfma_f32_16x16x32_bf16 v[92:95], v[96:99], v[4:7], v[92:95]
	v_mfma_f32_16x16x32_bf16 v[88:91], v[96:99], v[0:3], v[88:91]
	ds_read_b128 v[96:99], v108 offset:9984
	s_waitcnt lgkmcnt(0)
	v_mfma_f32_16x16x32_bf16 v[100:103], v[96:99], v[12:15], v[24:27]
	v_mfma_f32_16x16x32_bf16 v[96:99], v[96:99], v[20:23], v[28:31]
	v_mfma_f32_16x16x32_bf16 v[100:103], v[104:107], v[8:11], v[100:103]
	v_mfma_f32_16x16x32_bf16 v[96:99], v[104:107], v[16:19], v[96:99]
	ds_read_b128 v[104:107], v108 offset:10112
	s_waitcnt lgkmcnt(0)
	v_mfma_f32_16x16x32_bf16 v[100:103], v[104:107], v[4:7], v[100:103]
	v_mfma_f32_16x16x32_bf16 v[96:99], v[104:107], v[0:3], v[96:99]
	v_add3_u32 v104, s9, v176, v177
	v_add_u32_e32 v105, 0x6800, v104
	ds_read2_b64 v[84:87], v105 offset1:4
	v_exp_f32_e32 v106, v80
	v_exp_f32_e32 v107, v81
	s_waitcnt lgkmcnt(0)
	v_mfma_f32_16x16x32_bf16 v[80:83], v[84:87], v[76:79], v[32:35]
	v_cvt_pk_bf16_f32 v74, v106, v107
	v_add_u32_e32 v106, 0x7800, v104
	s_nop 0
	ds_read2_b64 v[32:35], v106 offset0:32 offset1:36
	v_add_u32_e32 v107, 0x8800, v104
	s_waitcnt lgkmcnt(0)
	v_mfma_f32_16x16x32_bf16 v[40:43], v[32:35], v[76:79], v[40:43]
	v_add_u32_e32 v104, 0x9800, v104
	v_mfma_f32_16x16x32_bf16 v[60:63], v[32:35], v[72:75], v[60:63]
	ds_read2_b64 v[32:35], v107 offset0:64 offset1:68
	s_waitcnt lgkmcnt(0)
	v_mfma_f32_16x16x32_bf16 v[44:47], v[32:35], v[76:79], v[44:47]
	v_mfma_f32_16x16x32_bf16 v[64:67], v[32:35], v[72:75], v[64:67]
	ds_read2_b64 v[32:35], v104 offset0:96 offset1:100
	s_waitcnt lgkmcnt(0)
	v_mfma_f32_16x16x32_bf16 v[48:51], v[32:35], v[76:79], v[48:51]
	v_mfma_f32_16x16x32_bf16 v[52:55], v[32:35], v[72:75], v[52:55]
	v_mov_b64_e32 v[32:33], s[76:77]
	v_mov_b64_e32 v[34:35], s[78:79]
	v_readlane_b32 s77, v255, 21
	v_mfma_f32_16x16x32_bf16 v[36:39], v[84:87], v[72:75], v[36:39]
	v_exp_f32_e32 v84, v88
	v_exp_f32_e32 v85, v89
	v_exp_f32_e32 v86, v90
	v_mfma_f32_16x16x32_bf16 v[68:71], v[32:35], v[76:79], v[68:71]
	v_exp_f32_e32 v76, v100
	v_exp_f32_e32 v77, v101
	v_exp_f32_e32 v78, v102
	v_mfma_f32_16x16x32_bf16 v[56:59], v[32:35], v[72:75], v[56:59]
	v_exp_f32_e32 v72, v92
	v_exp_f32_e32 v73, v93
	v_exp_f32_e32 v74, v94
	v_exp_f32_e32 v75, v95
	v_exp_f32_e32 v79, v103
	v_cvt_pk_bf16_f32 v72, v72, v73
	v_exp_f32_e32 v87, v91
	v_cvt_pk_bf16_f32 v73, v74, v75
	v_cvt_pk_bf16_f32 v74, v76, v77
	v_cvt_pk_bf16_f32 v75, v78, v79
	ds_read2_b64 v[76:79], v105 offset0:8 offset1:12
	v_exp_f32_e32 v88, v96
	v_exp_f32_e32 v89, v97
	v_exp_f32_e32 v90, v98
	v_exp_f32_e32 v91, v99
	v_cvt_pk_bf16_f32 v84, v84, v85
	v_cvt_pk_bf16_f32 v85, v86, v87
	v_cvt_pk_bf16_f32 v86, v88, v89
	v_cvt_pk_bf16_f32 v87, v90, v91
	s_waitcnt lgkmcnt(0)
	v_mfma_f32_16x16x32_bf16 v[80:83], v[76:79], v[72:75], v[80:83]
	ds_read_b128 v[92:95], v108 offset:16704
	ds_read_b128 v[100:103], v108 offset:20032
	s_mov_b32 s78, s38
	v_mfma_f32_16x16x32_bf16 v[36:39], v[76:79], v[84:87], v[36:39]
	ds_read2_b64 v[76:79], v106 offset0:40 offset1:44
	s_waitcnt lgkmcnt(0)
	v_mfma_f32_16x16x32_bf16 v[40:43], v[76:79], v[72:75], v[40:43]
	v_mfma_f32_16x16x32_bf16 v[60:63], v[76:79], v[84:87], v[60:63]
	ds_read2_b64 v[76:79], v107 offset0:72 offset1:76
	s_waitcnt lgkmcnt(0)
	v_mfma_f32_16x16x32_bf16 v[44:47], v[76:79], v[72:75], v[44:47]
	v_mfma_f32_16x16x32_bf16 v[64:67], v[76:79], v[84:87], v[64:67]
	ds_read2_b64 v[76:79], v104 offset0:104 offset1:108
	s_waitcnt lgkmcnt(0)
; DEV float ex2(float x) { return __builtin_amdgcn_exp2f(x); }
; DEV void attn_item(const Params& p, int bl, int head, int q0, int nkeys, char* smem, int tid) {
;     ...
;     for (int hh = 0; hh < 2; ++hh) {
;       f32x4 s[4][2];
; #pragma unroll
;       for (int kf = 0; kf < 4; ++kf) {
; #pragma unroll
;         for (int ks = 0; ks < 3; ++ks) {
;           bf16x8 a = *(const bf16x8*)(kb + (hh * 64 + kf * 16 + fr) * KROW + ks * 64 + fq * 16);
;           s[kf][0] = __builtin_amdgcn_mfma_f32_16x16x32_bf16(a, qf[0][ks], ks == 0 ? negm[0] : s[kf][0], 0, 0, 0);
;           s[kf][1] = __builtin_amdgcn_mfma_f32_16x16x32_bf16(a, qf[1][ks], ks == 0 ? negm[1] : s[kf][1], 0, 0, 0);
;         }
;       }
; #pragma unroll
;       for (int kk = 0; kk < 2; ++kk) {
;         bf16x8 pb[2];
; #pragma unroll
;         for (int qt = 0; qt < 2; ++qt) {
;           const float e0 = ex2(s[2 * kk][qt][0]), e1 = ex2(s[2 * kk][qt][1]), e2 = ex2(s[2 * kk][qt][2]), e3 = ex2(s[2 * kk][qt][3]);
;           const float e4 = ex2(s[2 * kk + 1][qt][0]), e5 = ex2(s[2 * kk + 1][qt][1]), e6 = ex2(s[2 * kk + 1][qt][2]), e7 = ex2(s[2 * kk + 1][qt][3]);
;           u32x4 cw = {pack2(e0, e1), pack2(e2, e3), pack2(e4, e5), pack2(e6, e7)};
;           pb[qt] = __builtin_bit_cast(bf16x8, cw);
;         }
;         lacc[0] = __builtin_amdgcn_mfma_f32_16x16x32_bf16(ones, pb[0], lacc[0], 0, 0, 0);
;         lacc[1] = __builtin_amdgcn_mfma_f32_16x16x32_bf16(ones, pb[1], lacc[1], 0, 0, 0);
; #pragma unroll
;         for (int dvf = 0; dvf < 4; ++dvf) {
;           const char* vp = vb + (dvf * 16 + fr) * VROW + (hh * 64 + kk * 32 + fq * 4) * 2;
;           const uint2 h0 = *(const uint2*)vp, h1 = *(const uint2*)(vp + 32);
;           u32x4 vw = {h0.x, h0.y, h1.x, h1.y};
;           const bf16x8 va = __builtin_bit_cast(bf16x8, vw);
;           o[dvf][0] = __builtin_amdgcn_mfma_f32_16x16x32_bf16(va, pb[0], o[dvf][0], 0, 0, 0);
;           o[dvf][1] = __builtin_amdgcn_mfma_f32_16x16x32_bf16(va, pb[1], o[dvf][1], 0, 0, 0);
;         }
;       }
;     }
;     if (t + 1 < nt) {
;       char* nb = smem + ((t + 1) & 1) * ASTG;
; #pragma unroll
;       for (int i = 0; i < 3; ++i) *(u32x4*)(nb + koff[i]) = kr[i];
; #pragma unroll
;       for (int i = 0; i < 2; ++i) *(u32x4*)(nb + KBYTES + voffl[i]) = vr[i];
;     }
;     __syncthreads();
;   }
	v_mfma_f32_16x16x32_bf16 v[48:51], v[76:79], v[72:75], v[48:51]
	v_mfma_f32_16x16x32_bf16 v[68:71], v[32:35], v[72:75], v[68:71]
	ds_read_b128 v[72:75], v108 offset:13312
	v_mfma_f32_16x16x32_bf16 v[52:55], v[76:79], v[84:87], v[52:55]
	v_mfma_f32_16x16x32_bf16 v[56:59], v[32:35], v[84:87], v[56:59]
	ds_read_b128 v[84:87], v108 offset:13376
	s_waitcnt lgkmcnt(1)
	v_mfma_f32_16x16x32_bf16 v[76:79], v[72:75], v[12:15], v[24:27]
	v_mfma_f32_16x16x32_bf16 v[72:75], v[72:75], v[20:23], v[28:31]
	s_waitcnt lgkmcnt(0)
	v_mfma_f32_16x16x32_bf16 v[76:79], v[84:87], v[8:11], v[76:79]
	v_mfma_f32_16x16x32_bf16 v[72:75], v[84:87], v[16:19], v[72:75]
	ds_read_b128 v[84:87], v108 offset:13440
	s_waitcnt lgkmcnt(0)
	v_mfma_f32_16x16x32_bf16 v[76:79], v[84:87], v[4:7], v[76:79]
	v_mfma_f32_16x16x32_bf16 v[72:75], v[84:87], v[0:3], v[72:75]
	ds_read_b128 v[84:87], v108 offset:16640
	s_waitcnt lgkmcnt(0)
	v_mfma_f32_16x16x32_bf16 v[88:91], v[84:87], v[12:15], v[24:27]
	v_mfma_f32_16x16x32_bf16 v[84:87], v[84:87], v[20:23], v[28:31]
	v_mfma_f32_16x16x32_bf16 v[88:91], v[92:95], v[8:11], v[88:91]
	v_mfma_f32_16x16x32_bf16 v[84:87], v[92:95], v[16:19], v[84:87]
	ds_read_b128 v[92:95], v108 offset:16768
	s_waitcnt lgkmcnt(0)
	v_mfma_f32_16x16x32_bf16 v[88:91], v[92:95], v[4:7], v[88:91]
	v_mfma_f32_16x16x32_bf16 v[84:87], v[92:95], v[0:3], v[84:87]
	ds_read_b128 v[92:95], v108 offset:19968
	s_waitcnt lgkmcnt(0)
	v_mfma_f32_16x16x32_bf16 v[96:99], v[92:95], v[12:15], v[24:27]
	v_mfma_f32_16x16x32_bf16 v[92:95], v[92:95], v[20:23], v[28:31]
	v_mfma_f32_16x16x32_bf16 v[96:99], v[100:103], v[8:11], v[96:99]
	v_mfma_f32_16x16x32_bf16 v[92:95], v[100:103], v[16:19], v[92:95]
	ds_read_b128 v[100:103], v108 offset:20096
	s_waitcnt lgkmcnt(0)
	v_mfma_f32_16x16x32_bf16 v[96:99], v[100:103], v[4:7], v[96:99]
	v_mfma_f32_16x16x32_bf16 v[92:95], v[100:103], v[0:3], v[92:95]
	ds_read_b128 v[100:103], v108 offset:23296
	s_waitcnt lgkmcnt(0)
	v_mfma_f32_16x16x32_bf16 v[12:15], v[100:103], v[12:15], v[24:27]
	s_nop 2
	ds_read_b128 v[24:27], v108 offset:23360
	v_mfma_f32_16x16x32_bf16 v[20:23], v[100:103], v[20:23], v[28:31]
	s_waitcnt lgkmcnt(0)
	v_mfma_f32_16x16x32_bf16 v[8:11], v[24:27], v[8:11], v[12:15]
	v_mfma_f32_16x16x32_bf16 v[12:15], v[24:27], v[16:19], v[20:23]
	ds_read_b128 v[16:19], v108 offset:23424
	v_exp_f32_e32 v24, v84
	v_exp_f32_e32 v25, v85
	s_waitcnt lgkmcnt(0)
	v_mfma_f32_16x16x32_bf16 v[4:7], v[16:19], v[4:7], v[8:11]
	s_nop 2
	v_exp_f32_e32 v8, v76
	v_exp_f32_e32 v9, v77
	v_exp_f32_e32 v10, v78
	v_mfma_f32_16x16x32_bf16 v[0:3], v[16:19], v[0:3], v[12:15]
	v_exp_f32_e32 v11, v79
	v_cvt_pk_bf16_f32 v8, v8, v9
	v_exp_f32_e32 v16, v72
	v_exp_f32_e32 v12, v88
	v_exp_f32_e32 v13, v89
	v_exp_f32_e32 v14, v90
	v_exp_f32_e32 v15, v91
	v_cvt_pk_bf16_f32 v9, v10, v11
	v_cvt_pk_bf16_f32 v10, v12, v13
	v_exp_f32_e32 v17, v73
	v_cvt_pk_bf16_f32 v11, v14, v15
	ds_read2_b64 v[12:15], v105 offset0:16 offset1:20
	v_exp_f32_e32 v18, v74
	v_exp_f32_e32 v19, v75
	v_exp_f32_e32 v26, v86
	v_exp_f32_e32 v27, v87
	v_cvt_pk_bf16_f32 v16, v16, v17
	v_cvt_pk_bf16_f32 v17, v18, v19
	v_cvt_pk_bf16_f32 v18, v24, v25
	v_cvt_pk_bf16_f32 v19, v26, v27
	s_waitcnt lgkmcnt(0)
	v_mfma_f32_16x16x32_bf16 v[20:23], v[12:15], v[8:11], v[80:83]
	ds_read2_b64 v[24:27], v106 offset0:48 offset1:52
	v_exp_f32_e32 v0, v0
	v_exp_f32_e32 v1, v1
	v_mfma_f32_16x16x32_bf16 v[12:15], v[12:15], v[16:19], v[36:39]
	v_exp_f32_e32 v2, v2
	v_exp_f32_e32 v3, v3
	v_exp_f32_e32 v4, v4
	ds_read2_b64 v[36:39], v107 offset0:80 offset1:84
	s_waitcnt lgkmcnt(1)
	v_mfma_f32_16x16x32_bf16 v[28:31], v[24:27], v[8:11], v[40:43]
	v_exp_f32_e32 v5, v5
	v_exp_f32_e32 v6, v6
	v_exp_f32_e32 v7, v7
	s_waitcnt lgkmcnt(0)
	v_mfma_f32_16x16x32_bf16 v[40:43], v[36:39], v[8:11], v[44:47]
	v_mov_b32_e32 v84, v174
	v_mfma_f32_16x16x32_bf16 v[44:47], v[36:39], v[16:19], v[64:67]
	ds_read2_b64 v[36:39], v104 offset0:112 offset1:116
	v_mfma_f32_16x16x32_bf16 v[24:27], v[24:27], v[16:19], v[60:63]
	s_nop 0
	v_cvt_pk_bf16_f32 v66, v4, v5
	v_cvt_pk_bf16_f32 v67, v6, v7
	ds_read2_b64 v[4:7], v105 offset0:24 offset1:28
	s_waitcnt lgkmcnt(1)
	v_mfma_f32_16x16x32_bf16 v[48:51], v[36:39], v[8:11], v[48:51]
	v_mfma_f32_16x16x32_bf16 v[60:63], v[32:35], v[8:11], v[68:71]
	v_exp_f32_e32 v8, v98
	v_exp_f32_e32 v9, v99
	v_exp_f32_e32 v10, v94
	v_cvt_pk_bf16_f32 v70, v0, v1
	v_cvt_pk_bf16_f32 v71, v2, v3
	ds_read2_b64 v[0:3], v106 offset0:56 offset1:60
	v_mfma_f32_16x16x32_bf16 v[52:55], v[36:39], v[16:19], v[52:55]
	v_exp_f32_e32 v36, v96
	v_exp_f32_e32 v37, v97
	v_cvt_pk_bf16_f32 v65, v8, v9
	v_exp_f32_e32 v8, v92
	v_exp_f32_e32 v9, v93
	v_exp_f32_e32 v11, v95
	v_cvt_pk_bf16_f32 v64, v36, v37
	v_mfma_f32_16x16x32_bf16 v[56:59], v[32:35], v[16:19], v[56:59]
	v_cvt_pk_bf16_f32 v68, v8, v9
	v_cvt_pk_bf16_f32 v69, v10, v11
	s_waitcnt lgkmcnt(0)
	v_mfma_f32_16x16x32_bf16 v[28:31], v[0:3], v[64:67], v[28:31]
	v_mfma_f32_16x16x32_bf16 v[8:11], v[0:3], v[68:71], v[24:27]
	ds_read2_b64 v[0:3], v107 offset0:88 offset1:92
	v_mfma_f32_16x16x32_bf16 v[36:39], v[4:7], v[64:67], v[20:23]
	s_nop 0
	v_or_b32_e32 v24, s8, v175
	v_mfma_f32_16x16x32_bf16 v[12:15], v[4:7], v[68:71], v[12:15]
	s_waitcnt lgkmcnt(0)
	v_mfma_f32_16x16x32_bf16 v[20:23], v[0:3], v[64:67], v[40:43]
	v_mfma_f32_16x16x32_bf16 v[4:7], v[0:3], v[68:71], v[44:47]
	ds_read2_b64 v[0:3], v104 offset0:120 offset1:124
	s_waitcnt lgkmcnt(0)
	s_barrier
	v_mfma_f32_16x16x32_bf16 v[16:19], v[0:3], v[64:67], v[48:51]
	v_add_u32_e32 v44, v24, v158
	v_mfma_f32_16x16x32_bf16 v[0:3], v[0:3], v[68:71], v[52:55]
	v_mfma_f32_16x16x32_bf16 v[40:43], v[32:35], v[64:67], v[60:63]
	v_mfma_f32_16x16x32_bf16 v[24:27], v[32:35], v[68:71], v[56:59]
	s_branch .LBB0_985
